# grid barrier waiters poll the cross-XCC arrival counter (TOP >= (round+1)*nx) instead of the generation word: one device-memory round trip less per barrier
# speedup vs baseline: 1.0051x; 1.0041x over previous
.LBB0_98:
	s_or_b64 exec, exec, s[10:11]
	v_cvt_f32_u32_e32 v4, v2
	s_waitcnt vmcnt(0)
	v_readfirstlane_b32 s3, v3
	v_sub_u32_e32 v3, 0, v2
	v_rcp_iflag_f32_e32 v4, v4
	v_add_u32_e32 v5, s3, v1
	v_mul_f32_e32 v4, 0x4f7ffffe, v4
	v_cvt_u32_f32_e32 v4, v4
	v_mul_lo_u32 v1, v3, v4
	v_mul_hi_u32 v1, v4, v1
	v_add_u32_e32 v1, v4, v1
	v_mul_hi_u32 v1, v5, v1
	v_mul_lo_u32 v3, v1, v2
	v_sub_u32_e32 v3, v5, v3
	v_add_u32_e32 v4, 1, v1
	v_cmp_ge_u32_e32 vcc, v3, v2
	s_nop 1
	v_cndmask_b32_e32 v1, v1, v4, vcc
	v_sub_u32_e32 v4, v3, v2
	v_cndmask_b32_e32 v3, v3, v4, vcc
	v_add_u32_e32 v4, 1, v1
	v_cmp_ge_u32_e32 vcc, v3, v2
	v_add_u32_e32 v3, 1, v5
	s_nop 0
	v_cndmask_b32_e32 v1, v1, v4, vcc
	v_mul_lo_u32 v4, v2, v1
	v_add_u32_e32 v2, v4, v2
	v_cmp_ne_u32_e32 vcc, v3, v2
	s_and_saveexec_b64 s[8:9], vcc
	s_xor_b64 s[8:9], exec, s[8:9]
	s_cbranch_execz .LBB0_112
	s_waitcnt lgkmcnt(0)
	v_mov_b32_e32 v0, 0x3400
	global_load_dword v0, v0, s[78:79] sc1
	s_add_u32 s12, s78, 0x3400
	s_addc_u32 s13, s79, 0
	s_waitcnt vmcnt(0)
	v_mov_b32_e32 v238, 0x20004
	ds_read_b32 v238, v238
	s_waitcnt lgkmcnt(0)
	v_add_u32_e32 v1, 1, v1
	v_mul_lo_u32 v1, v1, v238
	v_cmp_lt_u32_e32 vcc, v0, v1
	s_and_saveexec_b64 s[10:11], vcc
	s_cbranch_execz .LBB0_111
	s_mov_b32 s3, 1
	s_mov_b64 s[14:15], 0
	v_mov_b32_e32 v0, 0
	s_branch .LBB0_102

.LBB0_106:
	global_load_dword v2, v0, s[12:13] sc1
	s_add_i32 s3, s3, 1
	s_mov_b64 s[20:21], -1
	s_waitcnt vmcnt(0)
	v_cmp_ge_u32_e32 vcc, v2, v1
	s_orn2_b64 s[18:19], vcc, exec
	s_branch .LBB0_101

.LBB0_115:
	s_or_b64 exec, exec, s[10:11]
	v_cvt_f32_u32_e32 v3, v0
	s_waitcnt vmcnt(0)
	v_readfirstlane_b32 s3, v2
	s_add_u32 s10, s78, 0x3500
	s_addc_u32 s11, s79, 0
	v_rcp_iflag_f32_e32 v3, v3
	v_add_u32_e32 v1, s3, v1
	v_add_u32_e32 v4, 1, v1
	s_mov_b64 s[12:13], -1
	v_mul_f32_e32 v2, 0x4f7ffffe, v3
	v_cvt_u32_f32_e32 v2, v2
	v_sub_u32_e32 v3, 0, v0
	v_mul_lo_u32 v3, v3, v2
	v_mul_hi_u32 v3, v2, v3
	v_add_u32_e32 v2, v2, v3
	v_mul_hi_u32 v2, v1, v2
	v_mul_lo_u32 v3, v2, v0
	v_sub_u32_e32 v1, v1, v3
	v_add_u32_e32 v5, 1, v2
	v_cmp_ge_u32_e32 vcc, v1, v0
	v_sub_u32_e32 v3, v1, v0
	s_nop 0
	v_cndmask_b32_e32 v2, v2, v5, vcc
	v_cndmask_b32_e32 v1, v1, v3, vcc
	v_add_u32_e32 v3, 1, v2
	v_cmp_ge_u32_e32 vcc, v1, v0
	s_nop 1
	v_cndmask_b32_e32 v2, v2, v3, vcc
	v_mul_lo_u32 v1, v0, v2
	v_add_u32_e32 v0, v1, v0
	v_cmp_ne_u32_e32 vcc, v4, v0
	v_mov_b64_e32 v[0:1], s[10:11]
	s_and_saveexec_b64 s[8:9], vcc
	s_cbranch_execz .LBB0_127
	v_mov_b32_e32 v0, 0
	global_load_dword v1, v0, s[10:11] offset:-256 sc1
	s_mov_b64 s[16:17], 0
	s_waitcnt vmcnt(0)
	v_mov_b32_e32 v238, 0x20004
	ds_read_b32 v238, v238
	s_waitcnt lgkmcnt(0)
	v_add_u32_e32 v2, 1, v2
	v_mul_lo_u32 v2, v2, v238
	v_cmp_lt_u32_e32 vcc, v1, v2
	s_and_saveexec_b64 s[14:15], vcc
	s_cbranch_execz .LBB0_126
	s_add_u32 s12, s78, 0x200
	s_addc_u32 s13, s79, 0
	s_mov_b32 s3, 1
	s_branch .LBB0_119

.LBB0_123:
	global_load_dword v1, v0, s[10:11] offset:-256 sc1
	s_add_i32 s3, s3, 1
	s_mov_b64 s[20:21], -1
	s_waitcnt vmcnt(0)
	v_cmp_ge_u32_e32 vcc, v1, v2
	s_orn2_b64 s[26:27], vcc, exec
	s_branch .LBB0_118

.LBB0_152:
	s_waitcnt vmcnt(0)
	v_cndmask_b32_e64 v0, 0, 1, s[4:5]
	v_cmp_ne_u32_e64 s[0:1], 1, v0
	s_andn2_b64 vcc, exec, s[4:5]
	s_waitcnt lgkmcnt(0)
	v_writelane_b32 v235, s0, 41
	s_barrier
	s_mov_b32 s100, 0
	s_nop 0
	v_writelane_b32 v235, s1, 42
	s_cbranch_vccnz .LBB0_206
	v_mbcnt_lo_u32_b32 v0, -1, 0
	v_mbcnt_hi_u32_b32 v0, -1, v0
	s_nop 0
	v_cmp_eq_u32_e32 vcc, 0, v0
	s_and_saveexec_b64 s[0:1], vcc
	s_cbranch_execz .LBB0_205
	s_add_i32 s4, 0, 0x20000
	v_mov_b32_e32 v0, s4
	s_waitcnt vmcnt(0) expcnt(0) lgkmcnt(0)
	ds_read_b32 v2, v0
	s_add_i32 s4, 0, 0x20004
	v_mov_b32_e32 v0, s4
	ds_read_b32 v0, v0
	s_waitcnt lgkmcnt(1)
	v_cmp_ne_u32_e32 vcc, 0, v2
	s_cbranch_vccnz .LBB0_169
	v_readlane_b32 s4, v235, 0
	v_readlane_b32 s5, v235, 1
	v_readlane_b32 s6, v235, 2
	s_mul_i32 s18, s5, s6
	s_mul_i32 s18, s18, s4
	s_add_u32 s4, s78, 0x1000
	s_addc_u32 s5, s79, 0
	s_add_u32 s6, s78, 0x1100
	s_addc_u32 s7, s79, 0
	s_add_u32 s8, s78, 0x1200
	s_addc_u32 s9, s79, 0
	s_add_u32 s10, s78, 0x1300
	s_addc_u32 s11, s79, 0
	s_mov_b32 s19, 1
	v_mov_b32_e32 v16, 0
	s_branch .LBB0_157

.LBB0_171:
	s_or_b64 exec, exec, s[8:9]
	v_cvt_f32_u32_e32 v4, v2
	s_waitcnt vmcnt(0)
	v_readfirstlane_b32 s6, v3
	v_sub_u32_e32 v3, 0, v2
	v_rcp_iflag_f32_e32 v4, v4
	v_add_u32_e32 v5, s6, v1
	v_mul_f32_e32 v4, 0x4f7ffffe, v4
	v_cvt_u32_f32_e32 v4, v4
	v_mul_lo_u32 v1, v3, v4
	v_mul_hi_u32 v1, v4, v1
	v_add_u32_e32 v1, v4, v1
	v_mul_hi_u32 v1, v5, v1
	v_mul_lo_u32 v3, v1, v2
	v_sub_u32_e32 v3, v5, v3
	v_add_u32_e32 v4, 1, v1
	v_cmp_ge_u32_e32 vcc, v3, v2
	s_nop 1
	v_cndmask_b32_e32 v1, v1, v4, vcc
	v_sub_u32_e32 v4, v3, v2
	v_cndmask_b32_e32 v3, v3, v4, vcc
	v_add_u32_e32 v4, 1, v1
	v_cmp_ge_u32_e32 vcc, v3, v2
	v_add_u32_e32 v3, 1, v5
	s_nop 0
	v_cndmask_b32_e32 v1, v1, v4, vcc
	v_mul_lo_u32 v4, v2, v1
	v_add_u32_e32 v2, v4, v2
	v_cmp_ne_u32_e32 vcc, v3, v2
	s_and_saveexec_b64 s[6:7], vcc
	s_xor_b64 s[6:7], exec, s[6:7]
	s_cbranch_execz .LBB0_185
	s_waitcnt lgkmcnt(0)
	v_mov_b32_e32 v0, 0x3400
	global_load_dword v0, v0, s[78:79] sc1
	s_add_u32 s10, s78, 0x3400
	s_addc_u32 s11, s79, 0
	s_waitcnt vmcnt(0)
	v_mov_b32_e32 v238, 0x20004
	ds_read_b32 v238, v238
	s_waitcnt lgkmcnt(0)
	v_add_u32_e32 v1, 1, v1
	v_mul_lo_u32 v1, v1, v238
	v_cmp_lt_u32_e32 vcc, v0, v1
	s_cmp_lt_u32 s2, 16
	s_cbranch_scc0 ATB0_3866
	v_readfirstlane_b32 s100, v1
	s_mov_b64 vcc, 0

.LBB0_179:
	global_load_dword v2, v0, s[10:11] sc1
	s_add_i32 s22, s22, 1
	s_mov_b64 s[18:19], -1
	s_waitcnt vmcnt(0)
	v_cmp_ge_u32_e32 vcc, v2, v1
	s_orn2_b64 s[16:17], vcc, exec
	s_branch .LBB0_174

.LBB0_188:
	s_or_b64 exec, exec, s[8:9]
	v_cvt_f32_u32_e32 v3, v0
	s_waitcnt vmcnt(0)
	v_readfirstlane_b32 s6, v2
	s_add_u32 s8, s78, 0x3500
	s_addc_u32 s9, s79, 0
	v_rcp_iflag_f32_e32 v3, v3
	v_add_u32_e32 v1, s6, v1
	v_add_u32_e32 v4, 1, v1
	s_mov_b64 s[10:11], -1
	v_mul_f32_e32 v2, 0x4f7ffffe, v3
	v_cvt_u32_f32_e32 v2, v2
	v_sub_u32_e32 v3, 0, v0
	v_mul_lo_u32 v3, v3, v2
	v_mul_hi_u32 v3, v2, v3
	v_add_u32_e32 v2, v2, v3
	v_mul_hi_u32 v2, v1, v2
	v_mul_lo_u32 v3, v2, v0
	v_sub_u32_e32 v1, v1, v3
	v_add_u32_e32 v5, 1, v2
	v_cmp_ge_u32_e32 vcc, v1, v0
	v_sub_u32_e32 v3, v1, v0
	s_nop 0
	v_cndmask_b32_e32 v2, v2, v5, vcc
	v_cndmask_b32_e32 v1, v1, v3, vcc
	v_add_u32_e32 v3, 1, v2
	v_cmp_ge_u32_e32 vcc, v1, v0
	s_nop 1
	v_cndmask_b32_e32 v2, v2, v3, vcc
	v_mul_lo_u32 v1, v0, v2
	v_add_u32_e32 v0, v1, v0
	v_cmp_ne_u32_e32 vcc, v4, v0
	v_mov_b64_e32 v[0:1], s[8:9]
	s_and_saveexec_b64 s[6:7], vcc
	s_cbranch_execz .LBB0_200
	v_mov_b32_e32 v0, 0
	global_load_dword v1, v0, s[8:9] offset:-256 sc1
	s_mov_b64 s[14:15], 0
	s_waitcnt vmcnt(0)
	v_mov_b32_e32 v238, 0x20004
	ds_read_b32 v238, v238
	s_waitcnt lgkmcnt(0)
	v_add_u32_e32 v2, 1, v2
	v_mul_lo_u32 v2, v2, v238
	v_cmp_lt_u32_e32 vcc, v1, v2
	s_cmp_lt_u32 s2, 16
	s_cbranch_scc0 ATB0_4007
	v_readfirstlane_b32 s100, v2
	s_mov_b64 vcc, 0

.LBB0_196:
	global_load_dword v1, v0, s[8:9] offset:-256 sc1
	s_add_i32 s26, s26, 1
	s_mov_b64 s[18:19], -1
	s_waitcnt vmcnt(0)
	v_cmp_ge_u32_e32 vcc, v1, v2
	s_orn2_b64 s[22:23], vcc, exec
	s_branch .LBB0_191

.LBB0_213:
	v_lshl_add_u32 v128, s4, 8, v141
	v_ashrrev_i32_e32 v129, 31, v128
	v_lshl_add_u64 v[130:131], v[128:129], 2, s[88:89]
	global_load_dword v136, v[130:131], off
	global_load_dword v236, v[130:131], off offset:64
	global_load_dword v237, v[130:131], off offset:128
	global_load_dword v238, v[130:131], off offset:192
	global_load_dword v239, v[130:131], off offset:512
	global_load_dword v240, v[130:131], off offset:576
	global_load_dword v241, v[130:131], off offset:640
	global_load_dword v242, v[130:131], off offset:704
	v_ashrrev_i32_e32 v129, 1, v140
	s_lshl_b32 s1, s0, 8
	v_readlane_b32 s4, v235, 37
	v_and_b32_e32 v129, -8, v129
	s_or_b32 s1, s4, s1
	v_add_u32_e32 v134, s1, v129
	s_movk_i32 s0, 0x1040
	v_mov_b64_e32 v[132:133], s[52:53]
	v_ashrrev_i32_e32 v135, 31, v134
	v_mad_i64_i32 v[138:139], s[4:5], v128, s0, v[132:133]
	v_or_b32_e32 v140, 16, v128
	v_lshlrev_b64 v[134:135], 1, v[134:135]
	v_ashrrev_i32_e32 v141, 31, v140
	v_lshl_add_u64 v[138:139], v[138:139], 0, v[134:135]
	v_lshl_add_u64 v[142:143], v[140:141], 2, s[88:89]
	s_movk_i32 s1, 0x80
	v_writelane_b32 v235, s1, 45
	s_waitcnt vmcnt(0)
	v_pk_mul_f32 v[126:127], v[126:127], v[136:137] op_sel_hi:[1,0]
	v_pk_mul_f32 v[124:125], v[124:125], v[136:137] op_sel_hi:[1,0]
	v_pk_mul_f32 v[122:123], v[122:123], v[136:137] op_sel_hi:[1,0]
	v_pk_mul_f32 v[120:121], v[120:121], v[136:137] op_sel_hi:[1,0]
	v_pk_mul_f32 v[118:119], v[118:119], v[136:137] op_sel_hi:[1,0]
	v_pk_mul_f32 v[116:117], v[116:117], v[136:137] op_sel_hi:[1,0]
	v_pk_mul_f32 v[144:145], v[114:115], v[136:137] op_sel_hi:[1,0]
	v_pk_mul_f32 v[136:137], v[112:113], v[136:137] op_sel_hi:[1,0]
	v_cvt_pk_bf16_f32 v112, v124, v125
	v_cvt_pk_bf16_f32 v113, v126, v127
	v_cvt_pk_bf16_f32 v114, v120, v121
	v_cvt_pk_bf16_f32 v115, v122, v123
	global_store_dwordx4 v[138:139], v[112:115], off
	s_nop 1
	v_cvt_pk_bf16_f32 v112, v116, v117
	v_cvt_pk_bf16_f32 v113, v118, v119
	v_cvt_pk_bf16_f32 v114, v136, v137
	v_cvt_pk_bf16_f32 v115, v144, v145
	global_store_dwordx4 v[138:139], v[112:115], off offset:256
	s_nop 1
	v_mad_i64_i32 v[116:117], s[4:5], v140, s0, v[132:133]
	v_or_b32_e32 v114, 32, v128
	v_ashrrev_i32_e32 v115, 31, v114
	v_lshl_add_u64 v[116:117], v[116:117], 0, v[134:135]
	v_lshl_add_u64 v[118:119], v[114:115], 2, s[88:89]
	s_nop 1
	v_mov_b32_e32 v112, v236
	v_pk_mul_f32 v[110:111], v[110:111], v[112:113] op_sel_hi:[1,0]
	v_pk_mul_f32 v[108:109], v[108:109], v[112:113] op_sel_hi:[1,0]
	v_pk_mul_f32 v[106:107], v[106:107], v[112:113] op_sel_hi:[1,0]
	v_pk_mul_f32 v[104:105], v[104:105], v[112:113] op_sel_hi:[1,0]
	v_pk_mul_f32 v[102:103], v[102:103], v[112:113] op_sel_hi:[1,0]
	v_pk_mul_f32 v[100:101], v[100:101], v[112:113] op_sel_hi:[1,0]
	v_pk_mul_f32 v[120:121], v[98:99], v[112:113] op_sel_hi:[1,0]
	v_pk_mul_f32 v[112:113], v[96:97], v[112:113] op_sel_hi:[1,0]
	v_cvt_pk_bf16_f32 v96, v108, v109
	v_cvt_pk_bf16_f32 v97, v110, v111
	v_cvt_pk_bf16_f32 v98, v104, v105
	v_cvt_pk_bf16_f32 v99, v106, v107
	global_store_dwordx4 v[116:117], v[96:99], off
	s_nop 1
	v_cvt_pk_bf16_f32 v96, v100, v101
	v_cvt_pk_bf16_f32 v97, v102, v103
	v_cvt_pk_bf16_f32 v98, v112, v113
	v_cvt_pk_bf16_f32 v99, v120, v121
	global_store_dwordx4 v[116:117], v[96:99], off offset:256
	s_nop 1
	v_mad_i64_i32 v[100:101], s[4:5], v114, s0, v[132:133]
	v_or_b32_e32 v98, 48, v128
	v_ashrrev_i32_e32 v99, 31, v98
	v_lshl_add_u64 v[100:101], v[100:101], 0, v[134:135]
	v_lshl_add_u64 v[102:103], v[98:99], 2, s[88:89]
	s_nop 1
	v_mov_b32_e32 v96, v237
	v_pk_mul_f32 v[94:95], v[94:95], v[96:97] op_sel_hi:[1,0]
	v_pk_mul_f32 v[92:93], v[92:93], v[96:97] op_sel_hi:[1,0]
	v_pk_mul_f32 v[90:91], v[90:91], v[96:97] op_sel_hi:[1,0]
	v_pk_mul_f32 v[88:89], v[88:89], v[96:97] op_sel_hi:[1,0]
	v_pk_mul_f32 v[82:83], v[82:83], v[96:97] op_sel_hi:[1,0]
	v_pk_mul_f32 v[80:81], v[80:81], v[96:97] op_sel_hi:[1,0]
	v_pk_mul_f32 v[104:105], v[74:75], v[96:97] op_sel_hi:[1,0]
	v_pk_mul_f32 v[96:97], v[72:73], v[96:97] op_sel_hi:[1,0]
	v_cvt_pk_bf16_f32 v72, v92, v93
	v_cvt_pk_bf16_f32 v73, v94, v95
	v_cvt_pk_bf16_f32 v74, v88, v89
	v_cvt_pk_bf16_f32 v75, v90, v91
	global_store_dwordx4 v[100:101], v[72:75], off
	s_nop 1
	v_cvt_pk_bf16_f32 v72, v80, v81
	v_cvt_pk_bf16_f32 v73, v82, v83
	v_cvt_pk_bf16_f32 v74, v96, v97
	v_cvt_pk_bf16_f32 v75, v104, v105
	global_store_dwordx4 v[100:101], v[72:75], off offset:256
	s_nop 1
	s_nop 1
	v_mov_b32_e32 v72, v238
	v_pk_mul_f32 v[80:81], v[86:87], v[72:73] op_sel_hi:[1,0]
	v_mad_i64_i32 v[74:75], s[4:5], v98, s0, v[132:133]
	v_lshl_add_u64 v[74:75], v[74:75], 0, v[134:135]
	v_pk_mul_f32 v[82:83], v[84:85], v[72:73] op_sel_hi:[1,0]
	v_pk_mul_f32 v[78:79], v[78:79], v[72:73] op_sel_hi:[1,0]
	v_pk_mul_f32 v[76:77], v[76:77], v[72:73] op_sel_hi:[1,0]
	v_pk_mul_f32 v[70:71], v[70:71], v[72:73] op_sel_hi:[1,0]
	v_pk_mul_f32 v[68:69], v[68:69], v[72:73] op_sel_hi:[1,0]
	v_pk_mul_f32 v[84:85], v[66:67], v[72:73] op_sel_hi:[1,0]
	v_pk_mul_f32 v[72:73], v[64:65], v[72:73] op_sel_hi:[1,0]
	v_cvt_pk_bf16_f32 v64, v82, v83
	v_cvt_pk_bf16_f32 v65, v80, v81
	v_cvt_pk_bf16_f32 v66, v76, v77
	v_cvt_pk_bf16_f32 v67, v78, v79
	global_store_dwordx4 v[74:75], v[64:67], off
	s_nop 1
	v_cvt_pk_bf16_f32 v64, v68, v69
	v_cvt_pk_bf16_f32 v65, v70, v71
	v_cvt_pk_bf16_f32 v66, v72, v73
	v_cvt_pk_bf16_f32 v67, v84, v85
	global_store_dwordx4 v[74:75], v[64:67], off offset:256
	s_nop 1
	s_nop 0
	v_add_u32_e32 v65, 0x80, v128
	v_mad_i64_i32 v[66:67], s[4:5], v65, s0, v[132:133]
	v_lshl_add_u64 v[66:67], v[66:67], 0, v[134:135]
	s_nop 1
	v_mov_b32_e32 v64, v239
	v_pk_mul_f32 v[62:63], v[62:63], v[64:65] op_sel_hi:[1,0]
	v_pk_mul_f32 v[60:61], v[60:61], v[64:65] op_sel_hi:[1,0]
	v_pk_mul_f32 v[58:59], v[58:59], v[64:65] op_sel_hi:[1,0]
	v_pk_mul_f32 v[56:57], v[56:57], v[64:65] op_sel_hi:[1,0]
	v_pk_mul_f32 v[54:55], v[54:55], v[64:65] op_sel_hi:[1,0]
	v_pk_mul_f32 v[52:53], v[52:53], v[64:65] op_sel_hi:[1,0]
	v_pk_mul_f32 v[68:69], v[50:51], v[64:65] op_sel_hi:[1,0]
	v_pk_mul_f32 v[64:65], v[48:49], v[64:65] op_sel_hi:[1,0]
	v_cvt_pk_bf16_f32 v48, v60, v61
	v_cvt_pk_bf16_f32 v49, v62, v63
	v_cvt_pk_bf16_f32 v50, v56, v57
	v_cvt_pk_bf16_f32 v51, v58, v59
	global_store_dwordx4 v[66:67], v[48:51], off
	s_nop 1
	v_cvt_pk_bf16_f32 v48, v52, v53
	v_cvt_pk_bf16_f32 v49, v54, v55
	v_cvt_pk_bf16_f32 v50, v64, v65
	v_cvt_pk_bf16_f32 v51, v68, v69
	global_store_dwordx4 v[66:67], v[48:51], off offset:256
	s_nop 1
	s_nop 0
	v_add_u32_e32 v49, 0x90, v128
	v_mad_i64_i32 v[50:51], s[4:5], v49, s0, v[132:133]
	v_lshl_add_u64 v[50:51], v[50:51], 0, v[134:135]
	s_nop 1
	v_mov_b32_e32 v48, v240
	v_pk_mul_f32 v[46:47], v[46:47], v[48:49] op_sel_hi:[1,0]
	v_pk_mul_f32 v[44:45], v[44:45], v[48:49] op_sel_hi:[1,0]
	v_pk_mul_f32 v[42:43], v[42:43], v[48:49] op_sel_hi:[1,0]
	v_pk_mul_f32 v[40:41], v[40:41], v[48:49] op_sel_hi:[1,0]
	v_pk_mul_f32 v[38:39], v[38:39], v[48:49] op_sel_hi:[1,0]
	v_pk_mul_f32 v[36:37], v[36:37], v[48:49] op_sel_hi:[1,0]
	v_pk_mul_f32 v[52:53], v[34:35], v[48:49] op_sel_hi:[1,0]
	v_pk_mul_f32 v[48:49], v[32:33], v[48:49] op_sel_hi:[1,0]
	v_cvt_pk_bf16_f32 v32, v44, v45
	v_cvt_pk_bf16_f32 v33, v46, v47
	v_cvt_pk_bf16_f32 v34, v40, v41
	v_cvt_pk_bf16_f32 v35, v42, v43
	global_store_dwordx4 v[50:51], v[32:35], off
	s_nop 1
	v_cvt_pk_bf16_f32 v32, v36, v37
	v_cvt_pk_bf16_f32 v33, v38, v39
	v_cvt_pk_bf16_f32 v34, v48, v49
	v_cvt_pk_bf16_f32 v35, v52, v53
	global_store_dwordx4 v[50:51], v[32:35], off offset:256
	s_nop 1
	s_nop 0
	v_add_u32_e32 v33, 0xa0, v128
	v_mad_i64_i32 v[34:35], s[4:5], v33, s0, v[132:133]
	v_lshl_add_u64 v[34:35], v[34:35], 0, v[134:135]
	s_nop 1
	v_mov_b32_e32 v32, v241
	v_pk_mul_f32 v[30:31], v[30:31], v[32:33] op_sel_hi:[1,0]
	v_pk_mul_f32 v[28:29], v[28:29], v[32:33] op_sel_hi:[1,0]
	v_pk_mul_f32 v[26:27], v[26:27], v[32:33] op_sel_hi:[1,0]
	v_pk_mul_f32 v[24:25], v[24:25], v[32:33] op_sel_hi:[1,0]
	v_pk_mul_f32 v[22:23], v[22:23], v[32:33] op_sel_hi:[1,0]
	v_pk_mul_f32 v[20:21], v[20:21], v[32:33] op_sel_hi:[1,0]
	v_pk_mul_f32 v[36:37], v[18:19], v[32:33] op_sel_hi:[1,0]
	v_pk_mul_f32 v[32:33], v[16:17], v[32:33] op_sel_hi:[1,0]
	v_cvt_pk_bf16_f32 v16, v28, v29
	v_cvt_pk_bf16_f32 v17, v30, v31
	v_cvt_pk_bf16_f32 v18, v24, v25
	v_cvt_pk_bf16_f32 v19, v26, v27
	global_store_dwordx4 v[34:35], v[16:19], off
	s_nop 1
	v_cvt_pk_bf16_f32 v16, v20, v21
	v_cvt_pk_bf16_f32 v17, v22, v23
	v_cvt_pk_bf16_f32 v18, v32, v33
	v_cvt_pk_bf16_f32 v19, v36, v37
	global_store_dwordx4 v[34:35], v[16:19], off offset:256
	s_nop 1
	s_nop 0
	v_add_u32_e32 v17, 0xb0, v128
	v_mad_i64_i32 v[18:19], s[0:1], v17, s0, v[132:133]
	v_lshl_add_u64 v[18:19], v[18:19], 0, v[134:135]
	v_readlane_b32 s0, v235, 41
	v_readlane_b32 s1, v235, 42
	s_and_b64 vcc, exec, s[0:1]
	s_nop 1
	v_mov_b32_e32 v16, v242
	v_pk_mul_f32 v[14:15], v[14:15], v[16:17] op_sel_hi:[1,0]
	v_pk_mul_f32 v[12:13], v[12:13], v[16:17] op_sel_hi:[1,0]
	v_pk_mul_f32 v[10:11], v[10:11], v[16:17] op_sel_hi:[1,0]
	v_pk_mul_f32 v[8:9], v[8:9], v[16:17] op_sel_hi:[1,0]
	v_pk_mul_f32 v[6:7], v[6:7], v[16:17] op_sel_hi:[1,0]
	v_pk_mul_f32 v[4:5], v[4:5], v[16:17] op_sel_hi:[1,0]
	v_pk_mul_f32 v[20:21], v[2:3], v[16:17] op_sel_hi:[1,0]
	v_pk_mul_f32 v[16:17], v[0:1], v[16:17] op_sel_hi:[1,0]
	v_cvt_pk_bf16_f32 v0, v12, v13
	v_cvt_pk_bf16_f32 v1, v14, v15
	v_cvt_pk_bf16_f32 v2, v8, v9
	v_cvt_pk_bf16_f32 v3, v10, v11
	global_store_dwordx4 v[18:19], v[0:3], off
	s_nop 1
	v_cvt_pk_bf16_f32 v0, v4, v5
	v_cvt_pk_bf16_f32 v1, v6, v7
	v_cvt_pk_bf16_f32 v2, v16, v17
	v_cvt_pk_bf16_f32 v3, v20, v21
	global_store_dwordx4 v[18:19], v[0:3], off offset:256
	s_waitcnt vmcnt(0)
	s_barrier
	s_waitcnt vmcnt(0)
	s_barrier
	s_cbranch_vccnz .LBB0_228
	v_mbcnt_lo_u32_b32 v0, -1, 0
	v_mbcnt_hi_u32_b32 v0, -1, v0
	s_nop 0
	v_cmp_eq_u32_e32 vcc, 0, v0
	s_and_saveexec_b64 s[0:1], vcc
	s_cbranch_execz .LBB0_227
	v_mov_b32_e32 v236, 0x3400
	s_movk_i32 s101, 0x4000
ATD0_POLL:
	global_load_dword v237, v236, s[78:79] sc1
	s_waitcnt vmcnt(0)
	v_cmp_le_u32_e32 vcc, s100, v237
	s_cbranch_vccnz ATD0_DONE
	s_sleep 2
	s_add_i32 s101, s101, -1
	s_cmp_eq_u32 s101, 0
	s_cbranch_scc0 ATD0_POLL

.LBB0_326:
	s_or_b64 exec, exec, s[8:9]
	v_cvt_f32_u32_e32 v4, v2
	s_waitcnt vmcnt(0)
	v_readfirstlane_b32 s6, v3
	v_sub_u32_e32 v3, 0, v2
	v_rcp_iflag_f32_e32 v4, v4
	v_add_u32_e32 v5, s6, v1
	v_mul_f32_e32 v4, 0x4f7ffffe, v4
	v_cvt_u32_f32_e32 v4, v4
	v_mul_lo_u32 v1, v3, v4
	v_mul_hi_u32 v1, v4, v1
	v_add_u32_e32 v1, v4, v1
	v_mul_hi_u32 v1, v5, v1
	v_mul_lo_u32 v3, v1, v2
	v_sub_u32_e32 v3, v5, v3
	v_add_u32_e32 v4, 1, v1
	v_cmp_ge_u32_e32 vcc, v3, v2
	s_nop 1
	v_cndmask_b32_e32 v1, v1, v4, vcc
	v_sub_u32_e32 v4, v3, v2
	v_cndmask_b32_e32 v3, v3, v4, vcc
	v_add_u32_e32 v4, 1, v1
	v_cmp_ge_u32_e32 vcc, v3, v2
	v_add_u32_e32 v3, 1, v5
	s_nop 0
	v_cndmask_b32_e32 v1, v1, v4, vcc
	v_mul_lo_u32 v4, v2, v1
	v_add_u32_e32 v2, v4, v2
	v_cmp_ne_u32_e32 vcc, v3, v2
	s_and_saveexec_b64 s[6:7], vcc
	s_xor_b64 s[6:7], exec, s[6:7]
	s_cbranch_execz .LBB0_340
	s_waitcnt lgkmcnt(0)
	v_mov_b32_e32 v0, 0x3400
	global_load_dword v0, v0, s[78:79] sc1
	s_add_u32 s10, s78, 0x3400
	s_addc_u32 s11, s79, 0
	s_waitcnt vmcnt(0)
	v_mov_b32_e32 v238, 0x20004
	ds_read_b32 v238, v238
	s_waitcnt lgkmcnt(0)
	v_add_u32_e32 v1, 1, v1
	v_mul_lo_u32 v1, v1, v238
	v_cmp_lt_u32_e32 vcc, v0, v1
	s_and_saveexec_b64 s[8:9], vcc
	s_cbranch_execz .LBB0_339
	s_mov_b32 s22, 1
	s_mov_b64 s[12:13], 0
	v_mov_b32_e32 v0, 0
	s_branch .LBB0_330

.LBB0_343:
	s_or_b64 exec, exec, s[8:9]
	v_cvt_f32_u32_e32 v3, v0
	s_waitcnt vmcnt(0)
	v_readfirstlane_b32 s6, v2
	s_add_u32 s8, s78, 0x3500
	s_addc_u32 s9, s79, 0
	v_rcp_iflag_f32_e32 v3, v3
	v_add_u32_e32 v1, s6, v1
	v_add_u32_e32 v4, 1, v1
	s_mov_b64 s[10:11], -1
	v_mul_f32_e32 v2, 0x4f7ffffe, v3
	v_cvt_u32_f32_e32 v2, v2
	v_sub_u32_e32 v3, 0, v0
	v_mul_lo_u32 v3, v3, v2
	v_mul_hi_u32 v3, v2, v3
	v_add_u32_e32 v2, v2, v3
	v_mul_hi_u32 v2, v1, v2
	v_mul_lo_u32 v3, v2, v0
	v_sub_u32_e32 v1, v1, v3
	v_add_u32_e32 v5, 1, v2
	v_cmp_ge_u32_e32 vcc, v1, v0
	v_sub_u32_e32 v3, v1, v0
	s_nop 0
	v_cndmask_b32_e32 v2, v2, v5, vcc
	v_cndmask_b32_e32 v1, v1, v3, vcc
	v_add_u32_e32 v3, 1, v2
	v_cmp_ge_u32_e32 vcc, v1, v0
	s_nop 1
	v_cndmask_b32_e32 v2, v2, v3, vcc
	v_mul_lo_u32 v1, v0, v2
	v_add_u32_e32 v0, v1, v0
	v_cmp_ne_u32_e32 vcc, v4, v0
	v_mov_b64_e32 v[0:1], s[8:9]
	s_and_saveexec_b64 s[6:7], vcc
	s_cbranch_execz .LBB0_355
	v_mov_b32_e32 v0, 0
	global_load_dword v1, v0, s[8:9] offset:-256 sc1
	s_mov_b64 s[14:15], 0
	s_waitcnt vmcnt(0)
	v_mov_b32_e32 v238, 0x20004
	ds_read_b32 v238, v238
	s_waitcnt lgkmcnt(0)
	v_add_u32_e32 v2, 1, v2
	v_mul_lo_u32 v2, v2, v238
	v_cmp_lt_u32_e32 vcc, v1, v2
	s_and_saveexec_b64 s[12:13], vcc
	s_cbranch_execz .LBB0_354
	s_add_u32 s10, s78, 0x200
	s_addc_u32 s11, s79, 0
	s_mov_b32 s26, 1
	s_branch .LBB0_347

.LBB0_428:
	s_or_b64 exec, exec, s[8:9]
	s_waitcnt vmcnt(0)
	v_readfirstlane_b32 s6, v2
	v_cvt_f32_u32_e32 v2, v0
	v_sub_u32_e32 v3, 0, v0
	v_add_u32_e32 v1, s6, v1
	s_add_u32 s6, s78, 0x3500
	v_rcp_iflag_f32_e32 v2, v2
	s_addc_u32 s7, s79, 0
	s_mov_b64 s[10:11], -1
	v_mul_f32_e32 v2, 0x4f7ffffe, v2
	v_cvt_u32_f32_e32 v2, v2
	v_mul_lo_u32 v3, v3, v2
	v_mul_hi_u32 v3, v2, v3
	v_add_u32_e32 v2, v2, v3
	v_mul_hi_u32 v2, v1, v2
	v_mul_lo_u32 v3, v2, v0
	v_sub_u32_e32 v3, v1, v3
	v_cmp_ge_u32_e32 vcc, v3, v0
	v_add_u32_e32 v4, 1, v2
	v_add_u32_e32 v1, 1, v1
	v_cndmask_b32_e32 v2, v2, v4, vcc
	v_sub_u32_e32 v4, v3, v0
	v_cndmask_b32_e32 v3, v3, v4, vcc
	v_cmp_ge_u32_e32 vcc, v3, v0
	v_add_u32_e32 v3, 1, v2
	s_nop 0
	v_cndmask_b32_e32 v2, v2, v3, vcc
	v_mul_lo_u32 v3, v0, v2
	v_add_u32_e32 v0, v3, v0
	v_cmp_ne_u32_e32 vcc, v1, v0
	v_mov_b64_e32 v[0:1], s[6:7]
	s_and_saveexec_b64 s[8:9], vcc
	s_cbranch_execz .LBB0_440
	v_mov_b32_e32 v0, 0
	global_load_dword v1, v0, s[6:7] offset:-256 sc1
	s_mov_b64 s[14:15], 0
	s_waitcnt vmcnt(0)
	v_mov_b32_e32 v238, 0x20004
	ds_read_b32 v238, v238
	s_waitcnt lgkmcnt(0)
	v_add_u32_e32 v2, 1, v2
	v_mul_lo_u32 v2, v2, v238
	v_cmp_lt_u32_e32 vcc, v1, v2
	s_and_saveexec_b64 s[12:13], vcc
	s_cbranch_execz .LBB0_439
	s_add_u32 s10, s78, 0x200
	s_addc_u32 s11, s79, 0
	s_mov_b32 s26, 1
	s_branch .LBB0_432

.LBB0_436:
	global_load_dword v1, v0, s[6:7] offset:-256 sc1
	s_add_i32 s26, s26, 1
	s_mov_b64 s[18:19], -1
	s_waitcnt vmcnt(0)
	v_cmp_ge_u32_e32 vcc, v1, v2
	s_orn2_b64 s[22:23], vcc, exec
	s_branch .LBB0_431

.LBB0_501:
	s_or_b64 exec, exec, s[8:9]
	s_waitcnt vmcnt(0)
	v_readfirstlane_b32 s6, v2
	v_cvt_f32_u32_e32 v2, v0
	v_sub_u32_e32 v3, 0, v0
	v_add_u32_e32 v1, s6, v1
	s_add_u32 s6, s78, 0x3500
	v_rcp_iflag_f32_e32 v2, v2
	s_addc_u32 s7, s79, 0
	s_mov_b64 s[10:11], -1
	v_mul_f32_e32 v2, 0x4f7ffffe, v2
	v_cvt_u32_f32_e32 v2, v2
	v_mul_lo_u32 v3, v3, v2
	v_mul_hi_u32 v3, v2, v3
	v_add_u32_e32 v2, v2, v3
	v_mul_hi_u32 v2, v1, v2
	v_mul_lo_u32 v3, v2, v0
	v_sub_u32_e32 v3, v1, v3
	v_cmp_ge_u32_e32 vcc, v3, v0
	v_add_u32_e32 v4, 1, v2
	v_add_u32_e32 v1, 1, v1
	v_cndmask_b32_e32 v2, v2, v4, vcc
	v_sub_u32_e32 v4, v3, v0
	v_cndmask_b32_e32 v3, v3, v4, vcc
	v_cmp_ge_u32_e32 vcc, v3, v0
	v_add_u32_e32 v3, 1, v2
	s_nop 0
	v_cndmask_b32_e32 v2, v2, v3, vcc
	v_mul_lo_u32 v3, v0, v2
	v_add_u32_e32 v0, v3, v0
	v_cmp_ne_u32_e32 vcc, v1, v0
	v_mov_b64_e32 v[0:1], s[6:7]
	s_and_saveexec_b64 s[8:9], vcc
	s_cbranch_execz .LBB0_513
	v_mov_b32_e32 v0, 0
	global_load_dword v1, v0, s[6:7] offset:-256 sc1
	s_mov_b64 s[14:15], 0
	s_waitcnt vmcnt(0)
	v_mov_b32_e32 v238, 0x20004
	ds_read_b32 v238, v238
	s_waitcnt lgkmcnt(0)
	v_add_u32_e32 v2, 1, v2
	v_mul_lo_u32 v2, v2, v238
	v_cmp_lt_u32_e32 vcc, v1, v2
	s_and_saveexec_b64 s[12:13], vcc
	s_cbranch_execz .LBB0_512
	s_add_u32 s10, s78, 0x200
	s_addc_u32 s11, s79, 0
	s_mov_b32 s24, 1
	s_branch .LBB0_505

.LBB0_509:
	global_load_dword v1, v0, s[6:7] offset:-256 sc1
	s_add_i32 s24, s24, 1
	s_mov_b64 s[18:19], -1
	s_waitcnt vmcnt(0)
	v_cmp_ge_u32_e32 vcc, v1, v2
	s_orn2_b64 s[22:23], vcc, exec
	s_branch .LBB0_504

.LBB0_861:
	s_waitcnt vmcnt(0)
	v_readlane_b32 s0, v235, 41
	v_readlane_b32 s1, v235, 42
	s_and_b64 vcc, exec, s[0:1]
	s_waitcnt lgkmcnt(0)
	s_barrier
	s_mov_b32 s100, 0
	s_cbranch_vccnz .LBB0_915
	v_mbcnt_lo_u32_b32 v0, -1, 0
	v_mbcnt_hi_u32_b32 v0, -1, v0
	s_nop 0
	v_cmp_eq_u32_e32 vcc, 0, v0
	s_and_saveexec_b64 s[0:1], vcc
	s_cbranch_execz .LBB0_914
	s_add_i32 s4, 0, 0x20000
	v_mov_b32_e32 v0, s4
	s_waitcnt vmcnt(0) expcnt(0) lgkmcnt(0)
	ds_read_b32 v2, v0
	s_add_i32 s4, 0, 0x20004
	v_mov_b32_e32 v0, s4
	ds_read_b32 v0, v0
	s_waitcnt lgkmcnt(1)
	v_cmp_ne_u32_e32 vcc, 0, v2
	s_cbranch_vccnz .LBB0_878
	v_readlane_b32 s4, v235, 0
	v_readlane_b32 s5, v235, 1
	v_readlane_b32 s6, v235, 2
	s_mul_i32 s18, s5, s6
	s_mul_i32 s18, s18, s4
	s_add_u32 s4, s78, 0x1000
	s_addc_u32 s5, s79, 0
	s_add_u32 s6, s78, 0x1100
	s_addc_u32 s7, s79, 0
	s_add_u32 s8, s78, 0x1200
	s_addc_u32 s9, s79, 0
	s_add_u32 s10, s78, 0x1300
	s_addc_u32 s11, s79, 0
	s_mov_b32 s19, 1
	v_mov_b32_e32 v16, 0
	s_branch .LBB0_866

.LBB0_880:
	s_or_b64 exec, exec, s[8:9]
	v_cvt_f32_u32_e32 v4, v2
	s_waitcnt vmcnt(0)
	v_readfirstlane_b32 s6, v3
	v_sub_u32_e32 v3, 0, v2
	v_rcp_iflag_f32_e32 v4, v4
	v_add_u32_e32 v5, s6, v1
	v_mul_f32_e32 v4, 0x4f7ffffe, v4
	v_cvt_u32_f32_e32 v4, v4
	v_mul_lo_u32 v1, v3, v4
	v_mul_hi_u32 v1, v4, v1
	v_add_u32_e32 v1, v4, v1
	v_mul_hi_u32 v1, v5, v1
	v_mul_lo_u32 v3, v1, v2
	v_sub_u32_e32 v3, v5, v3
	v_add_u32_e32 v4, 1, v1
	v_cmp_ge_u32_e32 vcc, v3, v2
	s_nop 1
	v_cndmask_b32_e32 v1, v1, v4, vcc
	v_sub_u32_e32 v4, v3, v2
	v_cndmask_b32_e32 v3, v3, v4, vcc
	v_add_u32_e32 v4, 1, v1
	v_cmp_ge_u32_e32 vcc, v3, v2
	v_add_u32_e32 v3, 1, v5
	s_nop 0
	v_cndmask_b32_e32 v1, v1, v4, vcc
	v_mul_lo_u32 v4, v2, v1
	v_add_u32_e32 v2, v4, v2
	v_cmp_ne_u32_e32 vcc, v3, v2
	s_and_saveexec_b64 s[6:7], vcc
	s_xor_b64 s[6:7], exec, s[6:7]
	s_cbranch_execz .LBB0_894
	s_waitcnt lgkmcnt(0)
	v_mov_b32_e32 v0, 0x3400
	global_load_dword v0, v0, s[78:79] sc1
	s_add_u32 s10, s78, 0x3400
	s_addc_u32 s11, s79, 0
	s_waitcnt vmcnt(0)
	v_mov_b32_e32 v238, 0x20004
	ds_read_b32 v238, v238
	s_waitcnt lgkmcnt(0)
	v_add_u32_e32 v1, 1, v1
	v_mul_lo_u32 v1, v1, v238
	v_cmp_lt_u32_e32 vcc, v0, v1
	s_cmp_lt_u32 s2, 16
	s_cbranch_scc0 ATB1_24509
	v_readfirstlane_b32 s100, v1
	s_mov_b64 vcc, 0

.LBB0_897:
	s_or_b64 exec, exec, s[8:9]
	s_waitcnt vmcnt(0)
	v_readfirstlane_b32 s6, v2
	v_cvt_f32_u32_e32 v2, v0
	v_sub_u32_e32 v3, 0, v0
	v_add_u32_e32 v1, s6, v1
	s_add_u32 s6, s78, 0x3500
	v_rcp_iflag_f32_e32 v2, v2
	s_addc_u32 s7, s79, 0
	s_mov_b64 s[10:11], -1
	v_mul_f32_e32 v2, 0x4f7ffffe, v2
	v_cvt_u32_f32_e32 v2, v2
	v_mul_lo_u32 v3, v3, v2
	v_mul_hi_u32 v3, v2, v3
	v_add_u32_e32 v2, v2, v3
	v_mul_hi_u32 v2, v1, v2
	v_mul_lo_u32 v3, v2, v0
	v_sub_u32_e32 v3, v1, v3
	v_cmp_ge_u32_e32 vcc, v3, v0
	v_add_u32_e32 v4, 1, v2
	v_add_u32_e32 v1, 1, v1
	v_cndmask_b32_e32 v2, v2, v4, vcc
	v_sub_u32_e32 v4, v3, v0
	v_cndmask_b32_e32 v3, v3, v4, vcc
	v_cmp_ge_u32_e32 vcc, v3, v0
	v_add_u32_e32 v3, 1, v2
	s_nop 0
	v_cndmask_b32_e32 v2, v2, v3, vcc
	v_mul_lo_u32 v3, v0, v2
	v_add_u32_e32 v0, v3, v0
	v_cmp_ne_u32_e32 vcc, v1, v0
	v_mov_b64_e32 v[0:1], s[6:7]
	s_and_saveexec_b64 s[8:9], vcc
	s_cbranch_execz .LBB0_909
	v_mov_b32_e32 v0, 0
	global_load_dword v1, v0, s[6:7] offset:-256 sc1
	s_mov_b64 s[14:15], 0
	s_waitcnt vmcnt(0)
	v_mov_b32_e32 v238, 0x20004
	ds_read_b32 v238, v238
	s_waitcnt lgkmcnt(0)
	v_add_u32_e32 v2, 1, v2
	v_mul_lo_u32 v2, v2, v238
	v_cmp_lt_u32_e32 vcc, v1, v2
	s_cmp_lt_u32 s2, 16
	s_cbranch_scc0 ATB1_24649
	v_readfirstlane_b32 s100, v2
	s_mov_b64 vcc, 0

.LBB0_922:
	v_ashrrev_i32_e32 v128, 1, v140
	v_and_b32_e32 v129, -8, v128
	v_lshl_add_u32 v128, s0, 8, v141
	s_lshl_b32 s0, s4, 8
	v_readlane_b32 s1, v235, 37
	s_or_b32 s0, s1, s0
	v_add_u32_e32 v132, s0, v129
	v_ashrrev_i32_e32 v133, 31, v132
	s_movk_i32 s0, 0x1040
	v_mov_b64_e32 v[130:131], s[52:53]
	v_ashrrev_i32_e32 v129, 31, v128
	v_mad_i64_i32 v[134:135], s[4:5], v128, s0, v[130:131]
	v_lshlrev_b64 v[132:133], 1, v[132:133]
	v_lshl_add_u64 v[136:137], v[134:135], 0, v[132:133]
	v_lshl_add_u64 v[134:135], v[128:129], 2, s[88:89]
	global_load_dword v138, v[134:135], off
	global_load_dword v236, v[134:135], off offset:64
	global_load_dword v237, v[134:135], off offset:128
	global_load_dword v238, v[134:135], off offset:192
	global_load_dword v239, v[134:135], off offset:512
	global_load_dword v240, v[134:135], off offset:576
	global_load_dword v241, v[134:135], off offset:640
	global_load_dword v242, v[134:135], off offset:704
	s_waitcnt vmcnt(0)
	v_pk_mul_f32 v[126:127], v[126:127], v[138:139] op_sel_hi:[1,0]
	v_pk_mul_f32 v[124:125], v[124:125], v[138:139] op_sel_hi:[1,0]
	v_pk_mul_f32 v[140:141], v[122:123], v[138:139] op_sel_hi:[1,0]
	v_pk_mul_f32 v[122:123], v[120:121], v[138:139] op_sel_hi:[1,0]
	v_cvt_pk_bf16_f32 v120, v124, v125
	v_cvt_pk_bf16_f32 v121, v126, v127
	v_pk_mul_f32 v[116:117], v[116:117], v[138:139] op_sel_hi:[1,0]
	v_cvt_pk_bf16_f32 v122, v122, v123
	v_cvt_pk_bf16_f32 v123, v140, v141
	global_store_dwordx4 v[136:137], v[120:123], off
	v_pk_mul_f32 v[118:119], v[118:119], v[138:139] op_sel_hi:[1,0]
	s_nop 0
	v_pk_mul_f32 v[120:121], v[114:115], v[138:139] op_sel_hi:[1,0]
	v_pk_mul_f32 v[114:115], v[112:113], v[138:139] op_sel_hi:[1,0]
	v_cvt_pk_bf16_f32 v112, v116, v117
	v_cvt_pk_bf16_f32 v113, v118, v119
	s_nop 0
	v_cvt_pk_bf16_f32 v114, v114, v115
	v_cvt_pk_bf16_f32 v115, v120, v121
	global_store_dwordx4 v[136:137], v[112:115], off offset:256
	s_nop 1
	v_or_b32_e32 v112, 16, v128
	v_ashrrev_i32_e32 v113, 31, v112
	v_mad_i64_i32 v[114:115], s[4:5], v112, s0, v[130:131]
	v_lshl_add_u64 v[112:113], v[112:113], 2, s[88:89]
	s_nop 1
	v_lshl_add_u64 v[114:115], v[114:115], 0, v[132:133]
	s_nop 1
	v_mov_b32_e32 v112, v236
	v_pk_mul_f32 v[110:111], v[110:111], v[112:113] op_sel_hi:[1,0]
	v_pk_mul_f32 v[108:109], v[108:109], v[112:113] op_sel_hi:[1,0]
	v_pk_mul_f32 v[116:117], v[106:107], v[112:113] op_sel_hi:[1,0]
	v_pk_mul_f32 v[106:107], v[104:105], v[112:113] op_sel_hi:[1,0]
	v_cvt_pk_bf16_f32 v104, v108, v109
	v_cvt_pk_bf16_f32 v105, v110, v111
	v_pk_mul_f32 v[100:101], v[100:101], v[112:113] op_sel_hi:[1,0]
	v_cvt_pk_bf16_f32 v106, v106, v107
	v_cvt_pk_bf16_f32 v107, v116, v117
	global_store_dwordx4 v[114:115], v[104:107], off
	v_pk_mul_f32 v[102:103], v[102:103], v[112:113] op_sel_hi:[1,0]
	s_nop 0
	v_pk_mul_f32 v[104:105], v[98:99], v[112:113] op_sel_hi:[1,0]
	v_pk_mul_f32 v[98:99], v[96:97], v[112:113] op_sel_hi:[1,0]
	v_cvt_pk_bf16_f32 v96, v100, v101
	v_cvt_pk_bf16_f32 v97, v102, v103
	s_nop 0
	v_cvt_pk_bf16_f32 v98, v98, v99
	v_cvt_pk_bf16_f32 v99, v104, v105
	global_store_dwordx4 v[114:115], v[96:99], off offset:256
	s_nop 1
	v_or_b32_e32 v96, 32, v128
	v_ashrrev_i32_e32 v97, 31, v96
	v_mad_i64_i32 v[98:99], s[4:5], v96, s0, v[130:131]
	v_lshl_add_u64 v[96:97], v[96:97], 2, s[88:89]
	s_nop 1
	v_lshl_add_u64 v[98:99], v[98:99], 0, v[132:133]
	s_nop 1
	v_mov_b32_e32 v96, v237
	v_pk_mul_f32 v[94:95], v[94:95], v[96:97] op_sel_hi:[1,0]
	v_pk_mul_f32 v[92:93], v[92:93], v[96:97] op_sel_hi:[1,0]
	v_pk_mul_f32 v[100:101], v[90:91], v[96:97] op_sel_hi:[1,0]
	v_pk_mul_f32 v[90:91], v[88:89], v[96:97] op_sel_hi:[1,0]
	v_cvt_pk_bf16_f32 v88, v92, v93
	v_cvt_pk_bf16_f32 v89, v94, v95
	v_pk_mul_f32 v[84:85], v[84:85], v[96:97] op_sel_hi:[1,0]
	v_cvt_pk_bf16_f32 v90, v90, v91
	v_cvt_pk_bf16_f32 v91, v100, v101
	global_store_dwordx4 v[98:99], v[88:91], off
	v_pk_mul_f32 v[86:87], v[86:87], v[96:97] op_sel_hi:[1,0]
	s_nop 0
	v_pk_mul_f32 v[88:89], v[82:83], v[96:97] op_sel_hi:[1,0]
	v_pk_mul_f32 v[82:83], v[80:81], v[96:97] op_sel_hi:[1,0]
	v_cvt_pk_bf16_f32 v80, v84, v85
	v_cvt_pk_bf16_f32 v81, v86, v87
	s_nop 0
	v_cvt_pk_bf16_f32 v82, v82, v83
	v_cvt_pk_bf16_f32 v83, v88, v89
	global_store_dwordx4 v[98:99], v[80:83], off offset:256
	s_nop 1
	v_or_b32_e32 v80, 48, v128
	v_ashrrev_i32_e32 v81, 31, v80
	v_mad_i64_i32 v[82:83], s[4:5], v80, s0, v[130:131]
	v_lshl_add_u64 v[80:81], v[80:81], 2, s[88:89]
	s_nop 1
	v_lshl_add_u64 v[82:83], v[82:83], 0, v[132:133]
	s_nop 1
	v_mov_b32_e32 v80, v238
	v_pk_mul_f32 v[78:79], v[78:79], v[80:81] op_sel_hi:[1,0]
	v_pk_mul_f32 v[76:77], v[76:77], v[80:81] op_sel_hi:[1,0]
	v_pk_mul_f32 v[84:85], v[74:75], v[80:81] op_sel_hi:[1,0]
	v_pk_mul_f32 v[74:75], v[72:73], v[80:81] op_sel_hi:[1,0]
	v_cvt_pk_bf16_f32 v72, v76, v77
	v_cvt_pk_bf16_f32 v73, v78, v79
	v_pk_mul_f32 v[70:71], v[70:71], v[80:81] op_sel_hi:[1,0]
	v_cvt_pk_bf16_f32 v74, v74, v75
	v_cvt_pk_bf16_f32 v75, v84, v85
	global_store_dwordx4 v[82:83], v[72:75], off
	v_pk_mul_f32 v[68:69], v[68:69], v[80:81] op_sel_hi:[1,0]
	s_nop 0
	v_pk_mul_f32 v[72:73], v[66:67], v[80:81] op_sel_hi:[1,0]
	v_pk_mul_f32 v[66:67], v[64:65], v[80:81] op_sel_hi:[1,0]
	v_cvt_pk_bf16_f32 v64, v68, v69
	v_cvt_pk_bf16_f32 v65, v70, v71
	s_nop 0
	v_cvt_pk_bf16_f32 v66, v66, v67
	v_cvt_pk_bf16_f32 v67, v72, v73
	global_store_dwordx4 v[82:83], v[64:67], off offset:256
	s_nop 1
	s_nop 1
	v_mov_b32_e32 v66, v239
	v_pk_mul_f32 v[62:63], v[62:63], v[66:67] op_sel_hi:[1,0]
	v_add_u32_e32 v64, 0x80, v128
	v_mad_i64_i32 v[64:65], s[4:5], v64, s0, v[130:131]
	v_lshl_add_u64 v[64:65], v[64:65], 0, v[132:133]
	v_pk_mul_f32 v[60:61], v[60:61], v[66:67] op_sel_hi:[1,0]
	v_pk_mul_f32 v[68:69], v[58:59], v[66:67] op_sel_hi:[1,0]
	v_pk_mul_f32 v[58:59], v[56:57], v[66:67] op_sel_hi:[1,0]
	v_cvt_pk_bf16_f32 v56, v60, v61
	v_cvt_pk_bf16_f32 v57, v62, v63
	v_pk_mul_f32 v[54:55], v[54:55], v[66:67] op_sel_hi:[1,0]
	v_cvt_pk_bf16_f32 v58, v58, v59
	v_cvt_pk_bf16_f32 v59, v68, v69
	global_store_dwordx4 v[64:65], v[56:59], off
	v_pk_mul_f32 v[52:53], v[52:53], v[66:67] op_sel_hi:[1,0]
	s_nop 0
	v_pk_mul_f32 v[56:57], v[50:51], v[66:67] op_sel_hi:[1,0]
	v_pk_mul_f32 v[50:51], v[48:49], v[66:67] op_sel_hi:[1,0]
	v_cvt_pk_bf16_f32 v48, v52, v53
	v_cvt_pk_bf16_f32 v49, v54, v55
	s_nop 0
	v_cvt_pk_bf16_f32 v50, v50, v51
	v_cvt_pk_bf16_f32 v51, v56, v57
	global_store_dwordx4 v[64:65], v[48:51], off offset:256
	s_nop 1
	s_nop 1
	v_mov_b32_e32 v50, v240
	v_pk_mul_f32 v[46:47], v[46:47], v[50:51] op_sel_hi:[1,0]
	v_add_u32_e32 v48, 0x90, v128
	v_mad_i64_i32 v[48:49], s[4:5], v48, s0, v[130:131]
	v_lshl_add_u64 v[48:49], v[48:49], 0, v[132:133]
	v_pk_mul_f32 v[44:45], v[44:45], v[50:51] op_sel_hi:[1,0]
	v_pk_mul_f32 v[52:53], v[42:43], v[50:51] op_sel_hi:[1,0]
	v_pk_mul_f32 v[42:43], v[40:41], v[50:51] op_sel_hi:[1,0]
	v_cvt_pk_bf16_f32 v40, v44, v45
	v_cvt_pk_bf16_f32 v41, v46, v47
	v_pk_mul_f32 v[38:39], v[38:39], v[50:51] op_sel_hi:[1,0]
	v_cvt_pk_bf16_f32 v42, v42, v43
	v_cvt_pk_bf16_f32 v43, v52, v53
	global_store_dwordx4 v[48:49], v[40:43], off
	v_pk_mul_f32 v[36:37], v[36:37], v[50:51] op_sel_hi:[1,0]
	s_nop 0
	v_pk_mul_f32 v[40:41], v[34:35], v[50:51] op_sel_hi:[1,0]
	v_pk_mul_f32 v[34:35], v[32:33], v[50:51] op_sel_hi:[1,0]
	v_cvt_pk_bf16_f32 v32, v36, v37
	v_cvt_pk_bf16_f32 v33, v38, v39
	s_nop 0
	v_cvt_pk_bf16_f32 v34, v34, v35
	v_cvt_pk_bf16_f32 v35, v40, v41
	global_store_dwordx4 v[48:49], v[32:35], off offset:256
	s_nop 1
	s_nop 1
	v_mov_b32_e32 v34, v241
	v_pk_mul_f32 v[30:31], v[30:31], v[34:35] op_sel_hi:[1,0]
	v_add_u32_e32 v32, 0xa0, v128
	v_mad_i64_i32 v[32:33], s[4:5], v32, s0, v[130:131]
	v_lshl_add_u64 v[32:33], v[32:33], 0, v[132:133]
	v_pk_mul_f32 v[28:29], v[28:29], v[34:35] op_sel_hi:[1,0]
	v_pk_mul_f32 v[36:37], v[26:27], v[34:35] op_sel_hi:[1,0]
	v_pk_mul_f32 v[26:27], v[24:25], v[34:35] op_sel_hi:[1,0]
	v_cvt_pk_bf16_f32 v24, v28, v29
	v_cvt_pk_bf16_f32 v25, v30, v31
	v_pk_mul_f32 v[22:23], v[22:23], v[34:35] op_sel_hi:[1,0]
	v_cvt_pk_bf16_f32 v26, v26, v27
	v_cvt_pk_bf16_f32 v27, v36, v37
	global_store_dwordx4 v[32:33], v[24:27], off
	v_pk_mul_f32 v[20:21], v[20:21], v[34:35] op_sel_hi:[1,0]
	s_nop 0
	v_pk_mul_f32 v[24:25], v[18:19], v[34:35] op_sel_hi:[1,0]
	v_pk_mul_f32 v[18:19], v[16:17], v[34:35] op_sel_hi:[1,0]
	v_cvt_pk_bf16_f32 v16, v20, v21
	v_cvt_pk_bf16_f32 v17, v22, v23
	s_nop 0
	v_cvt_pk_bf16_f32 v18, v18, v19
	v_cvt_pk_bf16_f32 v19, v24, v25
	global_store_dwordx4 v[32:33], v[16:19], off offset:256
	s_nop 1
	s_nop 1
	v_mov_b32_e32 v18, v242
	v_pk_mul_f32 v[14:15], v[14:15], v[18:19] op_sel_hi:[1,0]
	v_add_u32_e32 v16, 0xb0, v128
	v_mad_i64_i32 v[16:17], s[0:1], v16, s0, v[130:131]
	v_lshl_add_u64 v[16:17], v[16:17], 0, v[132:133]
	v_pk_mul_f32 v[12:13], v[12:13], v[18:19] op_sel_hi:[1,0]
	v_pk_mul_f32 v[20:21], v[10:11], v[18:19] op_sel_hi:[1,0]
	v_pk_mul_f32 v[10:11], v[8:9], v[18:19] op_sel_hi:[1,0]
	v_cvt_pk_bf16_f32 v8, v12, v13
	v_cvt_pk_bf16_f32 v9, v14, v15
	v_pk_mul_f32 v[6:7], v[6:7], v[18:19] op_sel_hi:[1,0]
	v_cvt_pk_bf16_f32 v10, v10, v11
	v_cvt_pk_bf16_f32 v11, v20, v21
	global_store_dwordx4 v[16:17], v[8:11], off
	v_pk_mul_f32 v[4:5], v[4:5], v[18:19] op_sel_hi:[1,0]
	v_readlane_b32 s0, v235, 41
	v_pk_mul_f32 v[8:9], v[2:3], v[18:19] op_sel_hi:[1,0]
	v_pk_mul_f32 v[2:3], v[0:1], v[18:19] op_sel_hi:[1,0]
	v_cvt_pk_bf16_f32 v0, v4, v5
	v_cvt_pk_bf16_f32 v1, v6, v7
	v_readlane_b32 s1, v235, 42
	v_cvt_pk_bf16_f32 v2, v2, v3
	v_cvt_pk_bf16_f32 v3, v8, v9
	global_store_dwordx4 v[16:17], v[0:3], off offset:256
	s_waitcnt vmcnt(0)
	s_barrier
	s_waitcnt vmcnt(0)
	s_and_b64 vcc, exec, s[0:1]
	s_barrier
	s_cbranch_vccnz .LBB0_936
	v_mbcnt_lo_u32_b32 v0, -1, 0
	v_mbcnt_hi_u32_b32 v0, -1, v0
	s_nop 0
	v_cmp_eq_u32_e32 vcc, 0, v0
	s_and_saveexec_b64 s[0:1], vcc
	s_cbranch_execz .LBB0_935
	v_mov_b32_e32 v236, 0x3400
	s_movk_i32 s101, 0x4000
ATD1_POLL:
	global_load_dword v237, v236, s[78:79] sc1
	s_waitcnt vmcnt(0)
	v_cmp_le_u32_e32 vcc, s100, v237
	s_cbranch_vccnz ATD1_DONE
	s_sleep 2
	s_add_i32 s101, s101, -1
	s_cmp_eq_u32 s101, 0
	s_cbranch_scc0 ATD1_POLL

.LBB0_1286:
	s_or_b64 exec, exec, s[10:11]
	v_cvt_f32_u32_e32 v4, v2
	s_waitcnt vmcnt(0)
	v_readfirstlane_b32 s8, v3
	v_sub_u32_e32 v3, 0, v2
	v_rcp_iflag_f32_e32 v4, v4
	v_add_u32_e32 v5, s8, v1
	v_mul_f32_e32 v4, 0x4f7ffffe, v4
	v_cvt_u32_f32_e32 v4, v4
	v_mul_lo_u32 v1, v3, v4
	v_mul_hi_u32 v1, v4, v1
	v_add_u32_e32 v1, v4, v1
	v_mul_hi_u32 v1, v5, v1
	v_mul_lo_u32 v3, v1, v2
	v_sub_u32_e32 v3, v5, v3
	v_add_u32_e32 v4, 1, v1
	v_cmp_ge_u32_e32 vcc, v3, v2
	s_nop 1
	v_cndmask_b32_e32 v1, v1, v4, vcc
	v_sub_u32_e32 v4, v3, v2
	v_cndmask_b32_e32 v3, v3, v4, vcc
	v_add_u32_e32 v4, 1, v1
	v_cmp_ge_u32_e32 vcc, v3, v2
	v_add_u32_e32 v3, 1, v5
	s_nop 0
	v_cndmask_b32_e32 v1, v1, v4, vcc
	v_mul_lo_u32 v4, v2, v1
	v_add_u32_e32 v2, v4, v2
	v_cmp_ne_u32_e32 vcc, v3, v2
	s_and_saveexec_b64 s[8:9], vcc
	s_xor_b64 s[8:9], exec, s[8:9]
	s_cbranch_execz .LBB0_1300
	s_waitcnt lgkmcnt(0)
	v_mov_b32_e32 v0, 0x3400
	global_load_dword v0, v0, s[78:79] sc1
	s_add_u32 s12, s78, 0x3400
	s_addc_u32 s13, s79, 0
	s_waitcnt vmcnt(0)
	v_mov_b32_e32 v238, 0x20004
	ds_read_b32 v238, v238
	s_waitcnt lgkmcnt(0)
	v_add_u32_e32 v1, 1, v1
	v_mul_lo_u32 v1, v1, v238
	v_cmp_lt_u32_e32 vcc, v0, v1
	s_and_saveexec_b64 s[10:11], vcc
	s_cbranch_execz .LBB0_1299
	s_mov_b32 s24, 1
	s_mov_b64 s[14:15], 0
	v_mov_b32_e32 v0, 0
	s_branch .LBB0_1290

.LBB0_1294:
	global_load_dword v2, v0, s[12:13] sc1
	s_add_i32 s24, s24, 1
	s_mov_b64 s[20:21], -1
	s_waitcnt vmcnt(0)
	v_cmp_ge_u32_e32 vcc, v2, v1
	s_orn2_b64 s[18:19], vcc, exec
	s_branch .LBB0_1289

.LBB0_1303:
	s_or_b64 exec, exec, s[10:11]
	s_waitcnt vmcnt(0)
	v_readfirstlane_b32 s8, v2
	v_cvt_f32_u32_e32 v2, v0
	v_sub_u32_e32 v3, 0, v0
	v_add_u32_e32 v1, s8, v1
	s_add_u32 s8, s78, 0x3500
	v_rcp_iflag_f32_e32 v2, v2
	s_addc_u32 s9, s79, 0
	s_mov_b64 s[12:13], -1
	v_mul_f32_e32 v2, 0x4f7ffffe, v2
	v_cvt_u32_f32_e32 v2, v2
	v_mul_lo_u32 v3, v3, v2
	v_mul_hi_u32 v3, v2, v3
	v_add_u32_e32 v2, v2, v3
	v_mul_hi_u32 v2, v1, v2
	v_mul_lo_u32 v3, v2, v0
	v_sub_u32_e32 v3, v1, v3
	v_cmp_ge_u32_e32 vcc, v3, v0
	v_add_u32_e32 v4, 1, v2
	v_add_u32_e32 v1, 1, v1
	v_cndmask_b32_e32 v2, v2, v4, vcc
	v_sub_u32_e32 v4, v3, v0
	v_cndmask_b32_e32 v3, v3, v4, vcc
	v_cmp_ge_u32_e32 vcc, v3, v0
	v_add_u32_e32 v3, 1, v2
	s_nop 0
	v_cndmask_b32_e32 v2, v2, v3, vcc
	v_mul_lo_u32 v3, v0, v2
	v_add_u32_e32 v0, v3, v0
	v_cmp_ne_u32_e32 vcc, v1, v0
	v_mov_b64_e32 v[0:1], s[8:9]
	s_and_saveexec_b64 s[10:11], vcc
	s_cbranch_execz .LBB0_1315
	v_mov_b32_e32 v0, 0
	global_load_dword v1, v0, s[8:9] offset:-256 sc1
	s_mov_b64 s[16:17], 0
	s_waitcnt vmcnt(0)
	v_mov_b32_e32 v238, 0x20004
	ds_read_b32 v238, v238
	s_waitcnt lgkmcnt(0)
	v_add_u32_e32 v2, 1, v2
	v_mul_lo_u32 v2, v2, v238
	v_cmp_lt_u32_e32 vcc, v1, v2
	s_and_saveexec_b64 s[14:15], vcc
	s_cbranch_execz .LBB0_1314
	s_add_u32 s12, s78, 0x200
	s_addc_u32 s13, s79, 0
	s_mov_b32 s26, 1
	s_branch .LBB0_1307

.LBB0_1311:
	global_load_dword v1, v0, s[8:9] offset:-256 sc1
	s_add_i32 s26, s26, 1
	s_mov_b64 s[20:21], -1
	s_waitcnt vmcnt(0)
	v_cmp_ge_u32_e32 vcc, v1, v2
	s_orn2_b64 s[24:25], vcc, exec
	s_branch .LBB0_1306

.LBB0_1589:
	s_or_b64 exec, exec, s[8:9]
	v_cvt_f32_u32_e32 v4, v2
	s_waitcnt vmcnt(0)
	v_readfirstlane_b32 s6, v3
	v_sub_u32_e32 v3, 0, v2
	v_rcp_iflag_f32_e32 v4, v4
	v_add_u32_e32 v5, s6, v1
	v_mul_f32_e32 v4, 0x4f7ffffe, v4
	v_cvt_u32_f32_e32 v4, v4
	v_mul_lo_u32 v1, v3, v4
	v_mul_hi_u32 v1, v4, v1
	v_add_u32_e32 v1, v4, v1
	v_mul_hi_u32 v1, v5, v1
	v_mul_lo_u32 v3, v1, v2
	v_sub_u32_e32 v3, v5, v3
	v_add_u32_e32 v4, 1, v1
	v_cmp_ge_u32_e32 vcc, v3, v2
	s_nop 1
	v_cndmask_b32_e32 v1, v1, v4, vcc
	v_sub_u32_e32 v4, v3, v2
	v_cndmask_b32_e32 v3, v3, v4, vcc
	v_add_u32_e32 v4, 1, v1
	v_cmp_ge_u32_e32 vcc, v3, v2
	v_add_u32_e32 v3, 1, v5
	s_nop 0
	v_cndmask_b32_e32 v1, v1, v4, vcc
	v_mul_lo_u32 v4, v2, v1
	v_add_u32_e32 v2, v4, v2
	v_cmp_ne_u32_e32 vcc, v3, v2
	s_and_saveexec_b64 s[6:7], vcc
	s_xor_b64 s[6:7], exec, s[6:7]
	s_cbranch_execz .LBB0_1603
	s_waitcnt lgkmcnt(0)
	v_mov_b32_e32 v0, 0x3400
	global_load_dword v0, v0, s[78:79] sc1
	s_add_u32 s10, s78, 0x3400
	s_addc_u32 s11, s79, 0
	s_waitcnt vmcnt(0)
	v_mov_b32_e32 v238, 0x20004
	ds_read_b32 v238, v238
	s_waitcnt lgkmcnt(0)
	v_add_u32_e32 v1, 1, v1
	v_mul_lo_u32 v1, v1, v238
	v_cmp_lt_u32_e32 vcc, v0, v1
	s_cmp_lt_u32 s2, 16
	s_cbranch_scc0 ATB2_45117
	v_readfirstlane_b32 s100, v1
	s_mov_b64 vcc, 0

.LBB0_1606:
	s_or_b64 exec, exec, s[8:9]
	s_waitcnt vmcnt(0)
	v_readfirstlane_b32 s6, v2
	v_cvt_f32_u32_e32 v2, v0
	v_sub_u32_e32 v3, 0, v0
	v_add_u32_e32 v1, s6, v1
	s_add_u32 s6, s78, 0x3500
	v_rcp_iflag_f32_e32 v2, v2
	s_addc_u32 s7, s79, 0
	s_mov_b64 s[10:11], -1
	v_mul_f32_e32 v2, 0x4f7ffffe, v2
	v_cvt_u32_f32_e32 v2, v2
	v_mul_lo_u32 v3, v3, v2
	v_mul_hi_u32 v3, v2, v3
	v_add_u32_e32 v2, v2, v3
	v_mul_hi_u32 v2, v1, v2
	v_mul_lo_u32 v3, v2, v0
	v_sub_u32_e32 v3, v1, v3
	v_cmp_ge_u32_e32 vcc, v3, v0
	v_add_u32_e32 v4, 1, v2
	v_add_u32_e32 v1, 1, v1
	v_cndmask_b32_e32 v2, v2, v4, vcc
	v_sub_u32_e32 v4, v3, v0
	v_cndmask_b32_e32 v3, v3, v4, vcc
	v_cmp_ge_u32_e32 vcc, v3, v0
	v_add_u32_e32 v3, 1, v2
	s_nop 0
	v_cndmask_b32_e32 v2, v2, v3, vcc
	v_mul_lo_u32 v3, v0, v2
	v_add_u32_e32 v0, v3, v0
	v_cmp_ne_u32_e32 vcc, v1, v0
	v_mov_b64_e32 v[0:1], s[6:7]
	s_and_saveexec_b64 s[8:9], vcc
	s_cbranch_execz .LBB0_1618
	v_mov_b32_e32 v0, 0
	global_load_dword v1, v0, s[6:7] offset:-256 sc1
	s_mov_b64 s[14:15], 0
	s_waitcnt vmcnt(0)
	v_mov_b32_e32 v238, 0x20004
	ds_read_b32 v238, v238
	s_waitcnt lgkmcnt(0)
	v_add_u32_e32 v2, 1, v2
	v_mul_lo_u32 v2, v2, v238
	v_cmp_lt_u32_e32 vcc, v1, v2
	s_cmp_lt_u32 s2, 16
	s_cbranch_scc0 ATB2_45257
	v_readfirstlane_b32 s100, v2
	s_mov_b64 vcc, 0

ATD2_POLL:
	global_load_dword v237, v236, s[78:79] sc1
	s_waitcnt vmcnt(0)
	v_cmp_le_u32_e32 vcc, s100, v237
	s_cbranch_vccnz ATD2_DONE
	s_sleep 2
	s_add_i32 s101, s101, -1
	s_cmp_eq_u32 s101, 0
	s_cbranch_scc0 ATD2_POLL

.LBB0_2242:
	s_or_b64 exec, exec, s[8:9]
	v_cvt_f32_u32_e32 v3, v0
	s_waitcnt vmcnt(0)
	v_readfirstlane_b32 s6, v2
	s_add_u32 s8, s78, 0x3500
	s_addc_u32 s9, s79, 0
	v_rcp_iflag_f32_e32 v3, v3
	v_add_u32_e32 v1, s6, v1
	v_add_u32_e32 v4, 1, v1
	s_mov_b64 s[10:11], -1
	v_mul_f32_e32 v2, 0x4f7ffffe, v3
	v_cvt_u32_f32_e32 v2, v2
	v_sub_u32_e32 v3, 0, v0
	v_mul_lo_u32 v3, v3, v2
	v_mul_hi_u32 v3, v2, v3
	v_add_u32_e32 v2, v2, v3
	v_mul_hi_u32 v2, v1, v2
	v_mul_lo_u32 v3, v2, v0
	v_sub_u32_e32 v1, v1, v3
	v_add_u32_e32 v5, 1, v2
	v_cmp_ge_u32_e32 vcc, v1, v0
	v_sub_u32_e32 v3, v1, v0
	s_nop 0
	v_cndmask_b32_e32 v2, v2, v5, vcc
	v_cndmask_b32_e32 v1, v1, v3, vcc
	v_add_u32_e32 v3, 1, v2
	v_cmp_ge_u32_e32 vcc, v1, v0
	s_nop 1
	v_cndmask_b32_e32 v2, v2, v3, vcc
	v_mul_lo_u32 v1, v0, v2
	v_add_u32_e32 v0, v1, v0
	v_cmp_ne_u32_e32 vcc, v4, v0
	v_mov_b64_e32 v[0:1], s[8:9]
	s_and_saveexec_b64 s[6:7], vcc
	s_cbranch_execz .LBB0_2254
	v_mov_b32_e32 v0, 0
	global_load_dword v1, v0, s[8:9] offset:-256 sc1
	s_mov_b64 s[14:15], 0
	s_waitcnt vmcnt(0)
	v_mov_b32_e32 v238, 0x20004
	ds_read_b32 v238, v238
	s_waitcnt lgkmcnt(0)
	v_add_u32_e32 v2, 1, v2
	v_mul_lo_u32 v2, v2, v238
	v_cmp_lt_u32_e32 vcc, v1, v2
	s_and_saveexec_b64 s[12:13], vcc
	s_cbranch_execz .LBB0_2253
	s_add_u32 s10, s78, 0x200
	s_addc_u32 s11, s79, 0
	s_mov_b32 s24, 1
	s_branch .LBB0_2246

.LBB0_2250:
	global_load_dword v1, v0, s[8:9] offset:-256 sc1
	s_add_i32 s24, s24, 1
	s_mov_b64 s[18:19], -1
	s_waitcnt vmcnt(0)
	v_cmp_ge_u32_e32 vcc, v1, v2
	s_orn2_b64 s[22:23], vcc, exec
	s_branch .LBB0_2245

.LBB0_2298:
	s_or_b64 exec, exec, s[8:9]
	v_cvt_f32_u32_e32 v4, v2
	s_waitcnt vmcnt(0)
	v_readfirstlane_b32 s6, v3
	v_sub_u32_e32 v3, 0, v2
	v_rcp_iflag_f32_e32 v4, v4
	v_add_u32_e32 v5, s6, v1
	v_mul_f32_e32 v4, 0x4f7ffffe, v4
	v_cvt_u32_f32_e32 v4, v4
	v_mul_lo_u32 v1, v3, v4
	v_mul_hi_u32 v1, v4, v1
	v_add_u32_e32 v1, v4, v1
	v_mul_hi_u32 v1, v5, v1
	v_mul_lo_u32 v3, v1, v2
	v_sub_u32_e32 v3, v5, v3
	v_add_u32_e32 v4, 1, v1
	v_cmp_ge_u32_e32 vcc, v3, v2
	s_nop 1
	v_cndmask_b32_e32 v1, v1, v4, vcc
	v_sub_u32_e32 v4, v3, v2
	v_cndmask_b32_e32 v3, v3, v4, vcc
	v_add_u32_e32 v4, 1, v1
	v_cmp_ge_u32_e32 vcc, v3, v2
	v_add_u32_e32 v3, 1, v5
	s_nop 0
	v_cndmask_b32_e32 v1, v1, v4, vcc
	v_mul_lo_u32 v4, v2, v1
	v_add_u32_e32 v2, v4, v2
	v_cmp_ne_u32_e32 vcc, v3, v2
	s_and_saveexec_b64 s[6:7], vcc
	s_xor_b64 s[6:7], exec, s[6:7]
	s_cbranch_execz .LBB0_2312
	s_waitcnt lgkmcnt(0)
	v_mov_b32_e32 v0, 0x3400
	global_load_dword v0, v0, s[78:79] sc1
	s_add_u32 s10, s78, 0x3400
	s_addc_u32 s11, s79, 0
	s_waitcnt vmcnt(0)
	v_mov_b32_e32 v238, 0x20004
	ds_read_b32 v238, v238
	s_waitcnt lgkmcnt(0)
	v_add_u32_e32 v1, 1, v1
	v_mul_lo_u32 v1, v1, v238
	v_cmp_lt_u32_e32 vcc, v0, v1
	s_cmp_lt_u32 s2, 16
	s_cbranch_scc0 ATB3_65704
	v_readfirstlane_b32 s100, v1
	s_mov_b64 vcc, 0

.LBB0_2315:
	s_or_b64 exec, exec, s[8:9]
	v_cvt_f32_u32_e32 v3, v0
	s_waitcnt vmcnt(0)
	v_readfirstlane_b32 s6, v2
	s_add_u32 s8, s78, 0x3500
	s_addc_u32 s9, s79, 0
	v_rcp_iflag_f32_e32 v3, v3
	v_add_u32_e32 v1, s6, v1
	v_add_u32_e32 v4, 1, v1
	s_mov_b64 s[10:11], -1
	v_mul_f32_e32 v2, 0x4f7ffffe, v3
	v_cvt_u32_f32_e32 v2, v2
	v_sub_u32_e32 v3, 0, v0
	v_mul_lo_u32 v3, v3, v2
	v_mul_hi_u32 v3, v2, v3
	v_add_u32_e32 v2, v2, v3
	v_mul_hi_u32 v2, v1, v2
	v_mul_lo_u32 v3, v2, v0
	v_sub_u32_e32 v1, v1, v3
	v_add_u32_e32 v5, 1, v2
	v_cmp_ge_u32_e32 vcc, v1, v0
	v_sub_u32_e32 v3, v1, v0
	s_nop 0
	v_cndmask_b32_e32 v2, v2, v5, vcc
	v_cndmask_b32_e32 v1, v1, v3, vcc
	v_add_u32_e32 v3, 1, v2
	v_cmp_ge_u32_e32 vcc, v1, v0
	s_nop 1
	v_cndmask_b32_e32 v2, v2, v3, vcc
	v_mul_lo_u32 v1, v0, v2
	v_add_u32_e32 v0, v1, v0
	v_cmp_ne_u32_e32 vcc, v4, v0
	v_mov_b64_e32 v[0:1], s[8:9]
	s_and_saveexec_b64 s[6:7], vcc
	s_cbranch_execz .LBB0_2327
	v_mov_b32_e32 v0, 0
	global_load_dword v1, v0, s[8:9] offset:-256 sc1
	s_mov_b64 s[14:15], 0
	s_waitcnt vmcnt(0)
	v_mov_b32_e32 v238, 0x20004
	ds_read_b32 v238, v238
	s_waitcnt lgkmcnt(0)
	v_add_u32_e32 v2, 1, v2
	v_mul_lo_u32 v2, v2, v238
	v_cmp_lt_u32_e32 vcc, v1, v2
	s_cmp_lt_u32 s2, 16
	s_cbranch_scc0 ATB3_65845
	v_readfirstlane_b32 s100, v2
	s_mov_b64 vcc, 0

.LBB0_2340:
	v_lshl_add_u32 v128, s4, 8, v141
	v_ashrrev_i32_e32 v129, 31, v128
	v_lshl_add_u64 v[130:131], v[128:129], 2, s[88:89]
	global_load_dword v136, v[130:131], off
	global_load_dword v236, v[130:131], off offset:64
	global_load_dword v237, v[130:131], off offset:128
	global_load_dword v238, v[130:131], off offset:192
	global_load_dword v239, v[130:131], off offset:512
	global_load_dword v240, v[130:131], off offset:576
	global_load_dword v241, v[130:131], off offset:640
	global_load_dword v242, v[130:131], off offset:704
	v_ashrrev_i32_e32 v129, 1, v140
	s_lshl_b32 s1, s0, 8
	v_readlane_b32 s4, v235, 37
	v_and_b32_e32 v129, -8, v129
	s_or_b32 s1, s4, s1
	v_add_u32_e32 v134, s1, v129
	s_movk_i32 s0, 0x1040
	v_mov_b64_e32 v[132:133], s[52:53]
	v_ashrrev_i32_e32 v135, 31, v134
	v_mad_i64_i32 v[138:139], s[4:5], v128, s0, v[132:133]
	v_or_b32_e32 v140, 16, v128
	v_lshlrev_b64 v[134:135], 1, v[134:135]
	v_ashrrev_i32_e32 v141, 31, v140
	v_lshl_add_u64 v[138:139], v[138:139], 0, v[134:135]
	v_lshl_add_u64 v[142:143], v[140:141], 2, s[88:89]
	s_waitcnt vmcnt(0)
	v_pk_mul_f32 v[126:127], v[126:127], v[136:137] op_sel_hi:[1,0]
	v_pk_mul_f32 v[124:125], v[124:125], v[136:137] op_sel_hi:[1,0]
	v_pk_mul_f32 v[122:123], v[122:123], v[136:137] op_sel_hi:[1,0]
	v_pk_mul_f32 v[120:121], v[120:121], v[136:137] op_sel_hi:[1,0]
	v_pk_mul_f32 v[118:119], v[118:119], v[136:137] op_sel_hi:[1,0]
	v_pk_mul_f32 v[116:117], v[116:117], v[136:137] op_sel_hi:[1,0]
	v_pk_mul_f32 v[144:145], v[114:115], v[136:137] op_sel_hi:[1,0]
	v_pk_mul_f32 v[136:137], v[112:113], v[136:137] op_sel_hi:[1,0]
	v_cvt_pk_bf16_f32 v112, v124, v125
	v_cvt_pk_bf16_f32 v113, v126, v127
	v_cvt_pk_bf16_f32 v114, v120, v121
	v_cvt_pk_bf16_f32 v115, v122, v123
	global_store_dwordx4 v[138:139], v[112:115], off
	s_nop 1
	v_cvt_pk_bf16_f32 v112, v116, v117
	v_cvt_pk_bf16_f32 v113, v118, v119
	v_cvt_pk_bf16_f32 v114, v136, v137
	v_cvt_pk_bf16_f32 v115, v144, v145
	global_store_dwordx4 v[138:139], v[112:115], off offset:256
	s_nop 1
	v_mad_i64_i32 v[116:117], s[4:5], v140, s0, v[132:133]
	v_or_b32_e32 v114, 32, v128
	v_ashrrev_i32_e32 v115, 31, v114
	v_lshl_add_u64 v[116:117], v[116:117], 0, v[134:135]
	v_lshl_add_u64 v[118:119], v[114:115], 2, s[88:89]
	s_nop 1
	v_mov_b32_e32 v112, v236
	v_pk_mul_f32 v[110:111], v[110:111], v[112:113] op_sel_hi:[1,0]
	v_pk_mul_f32 v[108:109], v[108:109], v[112:113] op_sel_hi:[1,0]
	v_pk_mul_f32 v[106:107], v[106:107], v[112:113] op_sel_hi:[1,0]
	v_pk_mul_f32 v[104:105], v[104:105], v[112:113] op_sel_hi:[1,0]
	v_pk_mul_f32 v[102:103], v[102:103], v[112:113] op_sel_hi:[1,0]
	v_pk_mul_f32 v[100:101], v[100:101], v[112:113] op_sel_hi:[1,0]
	v_pk_mul_f32 v[120:121], v[98:99], v[112:113] op_sel_hi:[1,0]
	v_pk_mul_f32 v[112:113], v[96:97], v[112:113] op_sel_hi:[1,0]
	v_cvt_pk_bf16_f32 v96, v108, v109
	v_cvt_pk_bf16_f32 v97, v110, v111
	v_cvt_pk_bf16_f32 v98, v104, v105
	v_cvt_pk_bf16_f32 v99, v106, v107
	global_store_dwordx4 v[116:117], v[96:99], off
	s_nop 1
	v_cvt_pk_bf16_f32 v96, v100, v101
	v_cvt_pk_bf16_f32 v97, v102, v103
	v_cvt_pk_bf16_f32 v98, v112, v113
	v_cvt_pk_bf16_f32 v99, v120, v121
	global_store_dwordx4 v[116:117], v[96:99], off offset:256
	s_nop 1
	v_mad_i64_i32 v[100:101], s[4:5], v114, s0, v[132:133]
	v_or_b32_e32 v98, 48, v128
	v_ashrrev_i32_e32 v99, 31, v98
	v_lshl_add_u64 v[100:101], v[100:101], 0, v[134:135]
	v_lshl_add_u64 v[102:103], v[98:99], 2, s[88:89]
	s_nop 1
	v_mov_b32_e32 v96, v237
	v_pk_mul_f32 v[94:95], v[94:95], v[96:97] op_sel_hi:[1,0]
	v_pk_mul_f32 v[92:93], v[92:93], v[96:97] op_sel_hi:[1,0]
	v_pk_mul_f32 v[90:91], v[90:91], v[96:97] op_sel_hi:[1,0]
	v_pk_mul_f32 v[88:89], v[88:89], v[96:97] op_sel_hi:[1,0]
	v_pk_mul_f32 v[82:83], v[82:83], v[96:97] op_sel_hi:[1,0]
	v_pk_mul_f32 v[80:81], v[80:81], v[96:97] op_sel_hi:[1,0]
	v_pk_mul_f32 v[104:105], v[74:75], v[96:97] op_sel_hi:[1,0]
	v_pk_mul_f32 v[96:97], v[72:73], v[96:97] op_sel_hi:[1,0]
	v_cvt_pk_bf16_f32 v72, v92, v93
	v_cvt_pk_bf16_f32 v73, v94, v95
	v_cvt_pk_bf16_f32 v74, v88, v89
	v_cvt_pk_bf16_f32 v75, v90, v91
	global_store_dwordx4 v[100:101], v[72:75], off
	s_nop 1
	v_cvt_pk_bf16_f32 v72, v80, v81
	v_cvt_pk_bf16_f32 v73, v82, v83
	v_cvt_pk_bf16_f32 v74, v96, v97
	v_cvt_pk_bf16_f32 v75, v104, v105
	global_store_dwordx4 v[100:101], v[72:75], off offset:256
	s_nop 1
	s_nop 1
	v_mov_b32_e32 v72, v238
	v_pk_mul_f32 v[80:81], v[86:87], v[72:73] op_sel_hi:[1,0]
	v_mad_i64_i32 v[74:75], s[4:5], v98, s0, v[132:133]
	v_lshl_add_u64 v[74:75], v[74:75], 0, v[134:135]
	v_pk_mul_f32 v[82:83], v[84:85], v[72:73] op_sel_hi:[1,0]
	v_pk_mul_f32 v[78:79], v[78:79], v[72:73] op_sel_hi:[1,0]
	v_pk_mul_f32 v[76:77], v[76:77], v[72:73] op_sel_hi:[1,0]
	v_pk_mul_f32 v[70:71], v[70:71], v[72:73] op_sel_hi:[1,0]
	v_pk_mul_f32 v[68:69], v[68:69], v[72:73] op_sel_hi:[1,0]
	v_pk_mul_f32 v[84:85], v[66:67], v[72:73] op_sel_hi:[1,0]
	v_pk_mul_f32 v[72:73], v[64:65], v[72:73] op_sel_hi:[1,0]
	v_cvt_pk_bf16_f32 v64, v82, v83
	v_cvt_pk_bf16_f32 v65, v80, v81
	v_cvt_pk_bf16_f32 v66, v76, v77
	v_cvt_pk_bf16_f32 v67, v78, v79
	global_store_dwordx4 v[74:75], v[64:67], off
	s_nop 1
	v_cvt_pk_bf16_f32 v64, v68, v69
	v_cvt_pk_bf16_f32 v65, v70, v71
	v_cvt_pk_bf16_f32 v66, v72, v73
	v_cvt_pk_bf16_f32 v67, v84, v85
	global_store_dwordx4 v[74:75], v[64:67], off offset:256
	s_nop 1
	s_nop 0
	v_add_u32_e32 v65, 0x80, v128
	v_mad_i64_i32 v[66:67], s[4:5], v65, s0, v[132:133]
	v_lshl_add_u64 v[66:67], v[66:67], 0, v[134:135]
	s_nop 1
	v_mov_b32_e32 v64, v239
	v_pk_mul_f32 v[62:63], v[62:63], v[64:65] op_sel_hi:[1,0]
	v_pk_mul_f32 v[60:61], v[60:61], v[64:65] op_sel_hi:[1,0]
	v_pk_mul_f32 v[58:59], v[58:59], v[64:65] op_sel_hi:[1,0]
	v_pk_mul_f32 v[56:57], v[56:57], v[64:65] op_sel_hi:[1,0]
	v_pk_mul_f32 v[54:55], v[54:55], v[64:65] op_sel_hi:[1,0]
	v_pk_mul_f32 v[52:53], v[52:53], v[64:65] op_sel_hi:[1,0]
	v_pk_mul_f32 v[68:69], v[50:51], v[64:65] op_sel_hi:[1,0]
	v_pk_mul_f32 v[64:65], v[48:49], v[64:65] op_sel_hi:[1,0]
	v_cvt_pk_bf16_f32 v48, v60, v61
	v_cvt_pk_bf16_f32 v49, v62, v63
	v_cvt_pk_bf16_f32 v50, v56, v57
	v_cvt_pk_bf16_f32 v51, v58, v59
	global_store_dwordx4 v[66:67], v[48:51], off
	s_nop 1
	v_cvt_pk_bf16_f32 v48, v52, v53
	v_cvt_pk_bf16_f32 v49, v54, v55
	v_cvt_pk_bf16_f32 v50, v64, v65
	v_cvt_pk_bf16_f32 v51, v68, v69
	global_store_dwordx4 v[66:67], v[48:51], off offset:256
	s_nop 1
	s_nop 0
	v_add_u32_e32 v49, 0x90, v128
	v_mad_i64_i32 v[50:51], s[4:5], v49, s0, v[132:133]
	v_lshl_add_u64 v[50:51], v[50:51], 0, v[134:135]
	s_nop 1
	v_mov_b32_e32 v48, v240
	v_pk_mul_f32 v[46:47], v[46:47], v[48:49] op_sel_hi:[1,0]
	v_pk_mul_f32 v[44:45], v[44:45], v[48:49] op_sel_hi:[1,0]
	v_pk_mul_f32 v[42:43], v[42:43], v[48:49] op_sel_hi:[1,0]
	v_pk_mul_f32 v[40:41], v[40:41], v[48:49] op_sel_hi:[1,0]
	v_pk_mul_f32 v[38:39], v[38:39], v[48:49] op_sel_hi:[1,0]
	v_pk_mul_f32 v[36:37], v[36:37], v[48:49] op_sel_hi:[1,0]
	v_pk_mul_f32 v[52:53], v[34:35], v[48:49] op_sel_hi:[1,0]
	v_pk_mul_f32 v[48:49], v[32:33], v[48:49] op_sel_hi:[1,0]
	v_cvt_pk_bf16_f32 v32, v44, v45
	v_cvt_pk_bf16_f32 v33, v46, v47
	v_cvt_pk_bf16_f32 v34, v40, v41
	v_cvt_pk_bf16_f32 v35, v42, v43
	global_store_dwordx4 v[50:51], v[32:35], off
	s_nop 1
	v_cvt_pk_bf16_f32 v32, v36, v37
	v_cvt_pk_bf16_f32 v33, v38, v39
	v_cvt_pk_bf16_f32 v34, v48, v49
	v_cvt_pk_bf16_f32 v35, v52, v53
	global_store_dwordx4 v[50:51], v[32:35], off offset:256
	s_nop 1
	s_nop 0
	v_add_u32_e32 v33, 0xa0, v128
	v_mad_i64_i32 v[34:35], s[4:5], v33, s0, v[132:133]
	v_lshl_add_u64 v[34:35], v[34:35], 0, v[134:135]
	s_nop 1
	v_mov_b32_e32 v32, v241
	v_pk_mul_f32 v[30:31], v[30:31], v[32:33] op_sel_hi:[1,0]
	v_pk_mul_f32 v[28:29], v[28:29], v[32:33] op_sel_hi:[1,0]
	v_pk_mul_f32 v[26:27], v[26:27], v[32:33] op_sel_hi:[1,0]
	v_pk_mul_f32 v[24:25], v[24:25], v[32:33] op_sel_hi:[1,0]
	v_pk_mul_f32 v[22:23], v[22:23], v[32:33] op_sel_hi:[1,0]
	v_pk_mul_f32 v[20:21], v[20:21], v[32:33] op_sel_hi:[1,0]
	v_pk_mul_f32 v[36:37], v[18:19], v[32:33] op_sel_hi:[1,0]
	v_pk_mul_f32 v[32:33], v[16:17], v[32:33] op_sel_hi:[1,0]
	v_cvt_pk_bf16_f32 v16, v28, v29
	v_cvt_pk_bf16_f32 v17, v30, v31
	v_cvt_pk_bf16_f32 v18, v24, v25
	v_cvt_pk_bf16_f32 v19, v26, v27
	global_store_dwordx4 v[34:35], v[16:19], off
	s_nop 1
	v_cvt_pk_bf16_f32 v16, v20, v21
	v_cvt_pk_bf16_f32 v17, v22, v23
	v_cvt_pk_bf16_f32 v18, v32, v33
	v_cvt_pk_bf16_f32 v19, v36, v37
	global_store_dwordx4 v[34:35], v[16:19], off offset:256
	s_nop 1
	s_nop 0
	v_add_u32_e32 v17, 0xb0, v128
	v_mad_i64_i32 v[18:19], s[0:1], v17, s0, v[132:133]
	v_lshl_add_u64 v[18:19], v[18:19], 0, v[134:135]
	v_readlane_b32 s0, v235, 41
	v_readlane_b32 s1, v235, 42
	s_and_b64 vcc, exec, s[0:1]
	s_nop 1
	v_mov_b32_e32 v16, v242
	v_pk_mul_f32 v[14:15], v[14:15], v[16:17] op_sel_hi:[1,0]
	v_pk_mul_f32 v[12:13], v[12:13], v[16:17] op_sel_hi:[1,0]
	v_pk_mul_f32 v[10:11], v[10:11], v[16:17] op_sel_hi:[1,0]
	v_pk_mul_f32 v[8:9], v[8:9], v[16:17] op_sel_hi:[1,0]
	v_pk_mul_f32 v[6:7], v[6:7], v[16:17] op_sel_hi:[1,0]
	v_pk_mul_f32 v[4:5], v[4:5], v[16:17] op_sel_hi:[1,0]
	v_pk_mul_f32 v[20:21], v[2:3], v[16:17] op_sel_hi:[1,0]
	v_pk_mul_f32 v[16:17], v[0:1], v[16:17] op_sel_hi:[1,0]
	v_cvt_pk_bf16_f32 v0, v12, v13
	v_cvt_pk_bf16_f32 v1, v14, v15
	v_cvt_pk_bf16_f32 v2, v8, v9
	v_cvt_pk_bf16_f32 v3, v10, v11
	global_store_dwordx4 v[18:19], v[0:3], off
	s_nop 1
	v_cvt_pk_bf16_f32 v0, v4, v5
	v_cvt_pk_bf16_f32 v1, v6, v7
	v_cvt_pk_bf16_f32 v2, v16, v17
	v_cvt_pk_bf16_f32 v3, v20, v21
	global_store_dwordx4 v[18:19], v[0:3], off offset:256
	s_waitcnt vmcnt(0)
	s_barrier
	s_waitcnt vmcnt(0)
	s_barrier
	s_cbranch_vccnz .LBB0_2354
	v_mbcnt_lo_u32_b32 v0, -1, 0
	v_mbcnt_hi_u32_b32 v0, -1, v0
	s_nop 0
	v_cmp_eq_u32_e32 vcc, 0, v0
	s_and_saveexec_b64 s[0:1], vcc
	s_cbranch_execz .LBB0_2353
	v_mov_b32_e32 v236, 0x3400
	s_movk_i32 s101, 0x4000
ATD3_POLL:
	global_load_dword v237, v236, s[78:79] sc1
	s_waitcnt vmcnt(0)
	v_cmp_le_u32_e32 vcc, s100, v237
	s_cbranch_vccnz ATD3_DONE
	s_sleep 2
	s_add_i32 s101, s101, -1
	s_cmp_eq_u32 s101, 0
	s_cbranch_scc0 ATD3_POLL

.LBB0_2705:
	s_or_b64 exec, exec, s[10:11]
	v_cvt_f32_u32_e32 v4, v2
	s_waitcnt vmcnt(0)
	v_readfirstlane_b32 s6, v3
	v_sub_u32_e32 v3, 0, v2
	v_rcp_iflag_f32_e32 v4, v4
	v_add_u32_e32 v5, s6, v1
	v_mul_f32_e32 v4, 0x4f7ffffe, v4
	v_cvt_u32_f32_e32 v4, v4
	v_mul_lo_u32 v1, v3, v4
	v_mul_hi_u32 v1, v4, v1
	v_add_u32_e32 v1, v4, v1
	v_mul_hi_u32 v1, v5, v1
	v_mul_lo_u32 v3, v1, v2
	v_sub_u32_e32 v3, v5, v3
	v_add_u32_e32 v4, 1, v1
	v_cmp_ge_u32_e32 vcc, v3, v2
	s_nop 1
	v_cndmask_b32_e32 v1, v1, v4, vcc
	v_sub_u32_e32 v4, v3, v2
	v_cndmask_b32_e32 v3, v3, v4, vcc
	v_add_u32_e32 v4, 1, v1
	v_cmp_ge_u32_e32 vcc, v3, v2
	v_add_u32_e32 v3, 1, v5
	s_nop 0
	v_cndmask_b32_e32 v1, v1, v4, vcc
	v_mul_lo_u32 v4, v2, v1
	v_add_u32_e32 v2, v4, v2
	v_cmp_ne_u32_e32 vcc, v3, v2
	s_and_saveexec_b64 s[6:7], vcc
	s_xor_b64 s[6:7], exec, s[6:7]
	s_cbranch_execz .LBB0_2719
	s_waitcnt lgkmcnt(0)
	v_mov_b32_e32 v0, 0x3400
	global_load_dword v0, v0, s[78:79] sc1
	s_add_u32 s12, s78, 0x3400
	s_addc_u32 s13, s79, 0
	s_waitcnt vmcnt(0)
	v_mov_b32_e32 v238, 0x20004
	ds_read_b32 v238, v238
	s_waitcnt lgkmcnt(0)
	v_add_u32_e32 v1, 1, v1
	v_mul_lo_u32 v1, v1, v238
	v_cmp_lt_u32_e32 vcc, v0, v1
	s_and_saveexec_b64 s[10:11], vcc
	s_cbranch_execz .LBB0_2718
	s_mov_b32 s24, 1
	s_mov_b64 s[14:15], 0
	v_mov_b32_e32 v0, 0
	s_branch .LBB0_2709

.LBB0_2722:
	s_or_b64 exec, exec, s[10:11]
	v_cvt_f32_u32_e32 v3, v0
	s_waitcnt vmcnt(0)
	v_readfirstlane_b32 s6, v2
	s_add_u32 s10, s78, 0x3500
	s_addc_u32 s11, s79, 0
	v_rcp_iflag_f32_e32 v3, v3
	v_add_u32_e32 v1, s6, v1
	v_add_u32_e32 v4, 1, v1
	s_mov_b64 s[12:13], -1
	v_mul_f32_e32 v2, 0x4f7ffffe, v3
	v_cvt_u32_f32_e32 v2, v2
	v_sub_u32_e32 v3, 0, v0
	v_mul_lo_u32 v3, v3, v2
	v_mul_hi_u32 v3, v2, v3
	v_add_u32_e32 v2, v2, v3
	v_mul_hi_u32 v2, v1, v2
	v_mul_lo_u32 v3, v2, v0
	v_sub_u32_e32 v1, v1, v3
	v_add_u32_e32 v5, 1, v2
	v_cmp_ge_u32_e32 vcc, v1, v0
	v_sub_u32_e32 v3, v1, v0
	s_nop 0
	v_cndmask_b32_e32 v2, v2, v5, vcc
	v_cndmask_b32_e32 v1, v1, v3, vcc
	v_add_u32_e32 v3, 1, v2
	v_cmp_ge_u32_e32 vcc, v1, v0
	s_nop 1
	v_cndmask_b32_e32 v2, v2, v3, vcc
	v_mul_lo_u32 v1, v0, v2
	v_add_u32_e32 v0, v1, v0
	v_cmp_ne_u32_e32 vcc, v4, v0
	v_mov_b64_e32 v[0:1], s[10:11]
	s_and_saveexec_b64 s[6:7], vcc
	s_cbranch_execz .LBB0_2734
	v_mov_b32_e32 v0, 0
	global_load_dword v1, v0, s[10:11] offset:-256 sc1
	s_mov_b64 s[16:17], 0
	s_waitcnt vmcnt(0)
	v_mov_b32_e32 v238, 0x20004
	ds_read_b32 v238, v238
	s_waitcnt lgkmcnt(0)
	v_add_u32_e32 v2, 1, v2
	v_mul_lo_u32 v2, v2, v238
	v_cmp_lt_u32_e32 vcc, v1, v2
	s_and_saveexec_b64 s[14:15], vcc
	s_cbranch_execz .LBB0_2733
	s_add_u32 s12, s78, 0x200
	s_addc_u32 s13, s79, 0
	s_mov_b32 s26, 1
	s_branch .LBB0_2726

.LBB0_2730:
	global_load_dword v1, v0, s[10:11] offset:-256 sc1
	s_add_i32 s26, s26, 1
	s_mov_b64 s[20:21], -1
	s_waitcnt vmcnt(0)
	v_cmp_ge_u32_e32 vcc, v1, v2
	s_orn2_b64 s[24:25], vcc, exec
	s_branch .LBB0_2725

.LBB0_2814:
	s_or_b64 exec, exec, s[6:7]
	v_cvt_f32_u32_e32 v4, v2
	s_waitcnt vmcnt(0)
	v_readfirstlane_b32 s4, v3
	v_sub_u32_e32 v3, 0, v2
	v_rcp_iflag_f32_e32 v4, v4
	v_add_u32_e32 v5, s4, v1
	v_mul_f32_e32 v4, 0x4f7ffffe, v4
	v_cvt_u32_f32_e32 v4, v4
	v_mul_lo_u32 v1, v3, v4
	v_mul_hi_u32 v1, v4, v1
	v_add_u32_e32 v1, v4, v1
	v_mul_hi_u32 v1, v5, v1
	v_mul_lo_u32 v3, v1, v2
	v_sub_u32_e32 v3, v5, v3
	v_add_u32_e32 v4, 1, v1
	v_cmp_ge_u32_e32 vcc, v3, v2
	s_nop 1
	v_cndmask_b32_e32 v1, v1, v4, vcc
	v_sub_u32_e32 v4, v3, v2
	v_cndmask_b32_e32 v3, v3, v4, vcc
	v_add_u32_e32 v4, 1, v1
	v_cmp_ge_u32_e32 vcc, v3, v2
	v_add_u32_e32 v3, 1, v5
	s_nop 0
	v_cndmask_b32_e32 v1, v1, v4, vcc
	v_mul_lo_u32 v4, v2, v1
	v_add_u32_e32 v2, v4, v2
	v_cmp_ne_u32_e32 vcc, v3, v2
	s_and_saveexec_b64 s[4:5], vcc
	s_xor_b64 s[4:5], exec, s[4:5]
	s_cbranch_execz .LBB0_2828
	s_waitcnt lgkmcnt(0)
	v_mov_b32_e32 v0, 0x3400
	global_load_dword v0, v0, s[78:79] sc1
	s_add_u32 s8, s78, 0x3400
	s_addc_u32 s9, s79, 0
	s_waitcnt vmcnt(0)
	v_mov_b32_e32 v238, 0x20004
	ds_read_b32 v238, v238
	s_waitcnt lgkmcnt(0)
	v_add_u32_e32 v1, 1, v1
	v_mul_lo_u32 v1, v1, v238
	v_cmp_lt_u32_e32 vcc, v0, v1
	s_and_saveexec_b64 s[6:7], vcc
	s_cbranch_execz .LBB0_2827
	s_mov_b32 s20, 1
	s_mov_b64 s[10:11], 0
	v_mov_b32_e32 v0, 0
	s_branch .LBB0_2818

.LBB0_2822:
	global_load_dword v2, v0, s[8:9] sc1
	s_add_i32 s20, s20, 1
	s_mov_b64 s[16:17], -1
	s_waitcnt vmcnt(0)
	v_cmp_ge_u32_e32 vcc, v2, v1
	s_orn2_b64 s[14:15], vcc, exec
	s_branch .LBB0_2817

.LBB0_2831:
	s_or_b64 exec, exec, s[6:7]
	v_cvt_f32_u32_e32 v3, v0
	s_waitcnt vmcnt(0)
	v_readfirstlane_b32 s4, v2
	s_add_u32 s6, s78, 0x3500
	s_addc_u32 s7, s79, 0
	v_rcp_iflag_f32_e32 v3, v3
	v_add_u32_e32 v1, s4, v1
	v_add_u32_e32 v4, 1, v1
	s_mov_b64 s[8:9], -1
	v_mul_f32_e32 v2, 0x4f7ffffe, v3
	v_cvt_u32_f32_e32 v2, v2
	v_sub_u32_e32 v3, 0, v0
	v_mul_lo_u32 v3, v3, v2
	v_mul_hi_u32 v3, v2, v3
	v_add_u32_e32 v2, v2, v3
	v_mul_hi_u32 v2, v1, v2
	v_mul_lo_u32 v3, v2, v0
	v_sub_u32_e32 v1, v1, v3
	v_add_u32_e32 v5, 1, v2
	v_cmp_ge_u32_e32 vcc, v1, v0
	v_sub_u32_e32 v3, v1, v0
	s_nop 0
	v_cndmask_b32_e32 v2, v2, v5, vcc
	v_cndmask_b32_e32 v1, v1, v3, vcc
	v_add_u32_e32 v3, 1, v2
	v_cmp_ge_u32_e32 vcc, v1, v0
	s_nop 1
	v_cndmask_b32_e32 v2, v2, v3, vcc
	v_mul_lo_u32 v1, v0, v2
	v_add_u32_e32 v0, v1, v0
	v_cmp_ne_u32_e32 vcc, v4, v0
	v_mov_b64_e32 v[0:1], s[6:7]
	s_and_saveexec_b64 s[4:5], vcc
	s_cbranch_execz .LBB0_2843
	v_mov_b32_e32 v0, 0
	global_load_dword v1, v0, s[6:7] offset:-256 sc1
	s_mov_b64 s[12:13], 0
	s_waitcnt vmcnt(0)
	v_mov_b32_e32 v238, 0x20004
	ds_read_b32 v238, v238
	s_waitcnt lgkmcnt(0)
	v_add_u32_e32 v2, 1, v2
	v_mul_lo_u32 v2, v2, v238
	v_cmp_lt_u32_e32 vcc, v1, v2
	s_and_saveexec_b64 s[10:11], vcc
	s_cbranch_execz .LBB0_2842
	s_add_u32 s8, s78, 0x200
	s_addc_u32 s9, s79, 0
	s_mov_b32 s22, 1
	s_branch .LBB0_2835

.LBB0_2839:
	global_load_dword v1, v0, s[6:7] offset:-256 sc1
	s_add_i32 s22, s22, 1
	s_mov_b64 s[16:17], -1
	s_waitcnt vmcnt(0)
	v_cmp_ge_u32_e32 vcc, v1, v2
	s_orn2_b64 s[20:21], vcc, exec
	s_branch .LBB0_2834
